# v080 + same epilogue store coalescing (ds_bpermute lane transpose) in P9 in-proj GEMM (both epilogue variants)
# speedup vs baseline: 1.0244x; 1.0016x over previous
; #define G_STAGE(bufoff, gbase, voff) do { _Pragma("unroll") for (int _i = 0; _i < 2; ++_i) \
;         __builtin_amdgcn_global_load_lds((const unsigned*)((const char*)(gbase) + (voff)[_i]), (LAS unsigned*)(lds + (bufoff) + ldsw + _i * 8192), 16, 0, 0); } while (0)
; #define G_WAIT_V(n) asm volatile("s_waitcnt vmcnt(" #n ")" ::: "memory")
; #define G_BAR __builtin_amdgcn_s_barrier()
; template <bool PERM, class Dec, class Epi>
; DI void gemm_phase(LAS unsigned char* lds, const int nM, const int nN, const int K, const int lda, const int ldb, const Dec& dec, const Epi& epi, const int vb, const int panel = -1) {
;     ...
;     G_STAGE(G_SB(0, 0), cB, voffB); G_STAGE(G_SA(0, 0), cA, voffA); G_STAGE(G_SB(0, 1), cB + hstepB, voffB); G_STAGE(G_SA(0, 1), cA + hstepA, voffA);
;     if (wr == 1) G_BAR;
;     G_WAIT_V(4); G_BAR;
;     G_STAGE(G_SB(1, 0), cB + kstep, voffB); G_STAGE(G_SA(1, 0), cA + kstep, voffA); G_STAGE(G_SB(1, 1), cB + hstepB + kstep, voffB);
;     G_WAIT_V(6); G_BAR;
; template <int ACT>
; DI void epi_bf16(const f32x4 (&acc)[2][2][4][2], bf16_t* O, const int ldc, int wr, int wc, int fr, int fq, const float* ssrow = nullptr) {
; #pragma unroll
;     for (int ai = 0; ai < 2; ++ai)
; #pragma unroll
;         for (int m = 0; m < 4; ++m) {
;             bf16_t* rowp = O + (size_t)(ai * HALF + wr * 64 + m * 16 + fr) * ldc + wc * 32 + 8 * fq;
;             const float rsc = ssrow ? __builtin_amdgcn_rsqf(ssrow[ai * HALF + wr * 64 + m * 16 + fr] * (1.f / 1024.f) + EPS_) : 1.f;
.LBB0_747:
	v_mov_b32_e32 v143, v133
	v_lshl_add_u64 v[8:9], s[10:11], 0, v[142:143]
	v_mov_b32_e32 v139, v133
	v_lshl_add_u64 v[10:11], s[10:11], 0, v[138:139]
	v_mov_b32_e32 v145, v133
	s_add_i32 m0, s36, 0x18000
	v_lshl_add_u64 v[8:9], v[8:9], 0, s[48:49]
	v_lshl_add_u64 v[12:13], s[12:13], 0, v[144:145]
	v_mov_b32_e32 v141, v133
	s_waitcnt vmcnt(4)
	s_barrier
	global_load_lds_dwordx4 v[8:9], off
	v_lshl_add_u64 v[8:9], v[10:11], 0, s[48:49]
	s_add_i32 m0, s36, 0x1a000
	s_add_i32 s72, s36, 0x8000
	v_lshl_add_u64 v[14:15], s[12:13], 0, v[140:141]
	global_load_lds_dwordx4 v[8:9], off
	v_lshl_add_u64 v[8:9], v[12:13], 0, s[48:49]
	s_mov_b32 m0, s72
	s_add_i32 s73, s36, 0xa000
	global_load_lds_dwordx4 v[8:9], off
	v_lshl_add_u64 v[8:9], v[14:15], 0, s[48:49]
	s_mov_b32 m0, s73
	s_lshl_b32 s2, s2, 5
	global_load_lds_dwordx4 v[8:9], off
	s_add_i32 m0, s36, 0x1c000
	v_lshl_add_u64 v[8:9], s[46:47], 0, v[142:143]
	global_load_lds_dwordx4 v[8:9], off
	v_lshl_add_u64 v[8:9], s[46:47], 0, v[138:139]
	s_add_i32 m0, s36, 0x1e000
	v_and_b32_e32 v7, 15, v3
	global_load_lds_dwordx4 v[8:9], off
	v_lshrrev_b32_e32 v8, 1, v3
	v_and_b32_e32 v8, 24, v8
	v_lshlrev_b32_e32 v9, 1, v8
	v_lshlrev_b32_e32 v3, 2, v3
	s_and_b32 s74, s2, 0x60
	v_lshl_or_b32 v146, s3, 6, v7
	v_bfe_u32 v148, v3, 4, 4
	v_lshl_or_b32 v148, s3, 6, v148
	v_lshl_or_b32 v7, v7, 6, v9
	s_lshl_b32 s3, s3, 13
	v_and_b32_e32 v3, 32, v3
	s_lshl_b32 s2, s74, 7
	v_bitop3_b32 v9, v7, s3, v3 bitop3:0xde
	v_bitop3_b32 v177, v7, s2, v3 bitop3:0xde
	v_or_b32_e32 v3, 16, v148
	v_mad_i64_i32 v[150:151], s[2:3], v3, s63, 0
	v_or_b32_e32 v3, 32, v148
	v_mad_i64_i32 v[152:153], s[2:3], v3, s63, 0
	v_or_b32_e32 v3, 48, v148
	v_mad_i64_i32 v[154:155], s[2:3], v3, s63, 0
	v_add_u32_e32 v3, 0x80, v148
	v_mad_i64_i32 v[156:157], s[2:3], v3, s63, 0
	v_add_u32_e32 v3, 0x90, v148
	v_mad_i64_i32 v[158:159], s[2:3], v3, s63, 0
	v_add_u32_e32 v3, 0xa0, v148
	v_mad_i64_i32 v[160:161], s[2:3], v3, s63, 0
	v_add_u32_e32 v3, 0xb0, v148
	v_mad_i64_i32 v[162:163], s[2:3], v3, s63, 0
	v_lshlrev_b32_e32 v3, 14, v5
	v_and_b32_e32 v3, 0xffff8000, v3
	v_lshl_add_u32 v3, v4, 11, v3
	v_and_b32_e32 v4, 1, v5
	v_lshl_or_b32 v3, v4, 6, v3
	v_lshl_add_u32 v164, v6, 1, v3
	v_lshlrev_b32_e32 v3, 14, v0
	v_and_b32_e32 v3, 0xffff8000, v3
	s_waitcnt vmcnt(6)
	v_lshl_add_u32 v1, v1, 11, v3
	v_and_b32_e32 v0, 1, v0
	v_mad_i64_i32 v[148:149], s[2:3], v148, s63, 0
	v_lshl_or_b32 v0, v0, 6, v1
	v_ashrrev_i32_e32 v147, 31, v146
	v_mov_b32_e32 v165, v133
	v_lshl_add_u32 v166, v2, 1, v0
	v_mov_b32_e32 v167, v133
	s_mov_b32 s75, 0
	v_add_u32_e32 v178, 0, v9
	v_mbcnt_lo_u32_b32 v193, -1, 0
	v_mbcnt_hi_u32_b32 v193, -1, v193
	v_and_b32_e32 v132, 3, v193
	v_lshlrev_b32_e32 v132, 4, v132
	v_and_b32_e32 v193, 60, v193
	v_lshl_or_b32 v193, v132, 2, v193
	s_mov_b32 s4, s6
	s_mov_b32 s15, s64
	s_mov_b64 s[2:3], s[12:13]
	s_mov_b64 s[28:29], s[10:11]
	s_barrier
	s_branch .LBB0_749
.LBB0_748:
	s_lshl_b32 s2, s74, 1
	s_add_u32 s2, s28, s2
	s_addc_u32 s3, s29, 0
	v_lshl_add_u64 v[0:1], s[2:3], 0, v[132:133]
	v_lshl_add_u64 v[0:1], v[0:1], 0, v[162:163]
	v_cvt_pk_bf16_f32 v131, v170, v171
	ds_bpermute_b32 v128, v193, v128
	ds_bpermute_b32 v129, v193, v129
	ds_bpermute_b32 v130, v193, v130
	ds_bpermute_b32 v131, v193, v131
	s_and_b64 vcc, exec, s[42:43]
	s_mov_b32 s4, s52
	s_mov_b32 s15, s50
	s_mov_b64 s[2:3], s[54:55]
	s_mov_b64 s[28:29], s[58:59]
	s_waitcnt lgkmcnt(0)
	global_store_dwordx4 v[0:1], v[128:131], off offset:256
	s_cbranch_vccnz .LBB0_757

; #define G_STAGE(bufoff, gbase, voff) do { _Pragma("unroll") for (int _i = 0; _i < 2; ++_i) \
;         __builtin_amdgcn_global_load_lds((const unsigned*)((const char*)(gbase) + (voff)[_i]), (LAS unsigned*)(lds + (bufoff) + ldsw + _i * 8192), 16, 0, 0); } while (0)
; #define G_LDA(dst, b, h) do { _Pragma("unroll") for (int m = 0; m < 4; ++m) _Pragma("unroll") for (int k = 0; k < 2; ++k) dst[m][k] = *(const LAS bf16x8*)(lds + G_SA(b, h) + aoff + m * 2048 + k * 1024); } while (0)
; #define G_LDB(dst, b, h) do { _Pragma("unroll") for (int n = 0; n < 2; ++n) _Pragma("unroll") for (int k = 0; k < 2; ++k) dst[n][k] = *(const LAS bf16x8*)(lds + G_SB(b, h) + boff + n * 2048 + k * 1024); } while (0)
; #define G_MMA(ai, bj, At, Bt) do { __builtin_amdgcn_s_setprio(1); _Pragma("unroll") for (int m = 0; m < 4; ++m) _Pragma("unroll") for (int n = 0; n < 2; ++n) _Pragma("unroll") for (int k = 0; k < 2; ++k) \
;         acc[ai][bj][m][n] = __builtin_amdgcn_mfma_f32_16x16x32_bf16(Bt[n][k], At[m][k], acc[ai][bj][m][n], 0, 0, 0); __builtin_amdgcn_s_setprio(0); } while (0)
; #define G_WAIT_V(n) asm volatile("s_waitcnt vmcnt(" #n ")" ::: "memory")
; #define G_WAIT_L(n) asm volatile("s_waitcnt lgkmcnt(" #n ")" ::: "memory")
; #define G_BAR __builtin_amdgcn_s_barrier()
; #define G_SCHED __builtin_amdgcn_sched_barrier(0)
; template <bool PERM, class Dec, class Epi>
; DI void gemm_phase(LAS unsigned char* lds, const int nM, const int nN, const int K, const int lda, const int ldb, const Dec& dec, const Epi& epi, const int vb, const int panel = -1) {
;     ...
;             G_LDB(B0, 0, 0); G_SCHED; G_LDA(At, 0, 0); G_STAGE(G_SA(1, 1), a1 + hstepA, voffA);
;             G_WAIT_L(8); G_BAR; G_WAIT_L(0); G_MMA(0, 0, At, B0); G_BAR; G_SCHED;
;             G_LDB(B1, 0, 1); G_STAGE(G_SB(0, 0), b2, voffB);
;             G_BAR; G_WAIT_L(0); G_MMA(0, 1, At, B1); G_BAR;
;             G_LDA(At, 0, 1); G_STAGE(G_SA(0, 0), a2, voffA);
;             G_BAR; G_WAIT_L(0); G_MMA(1, 0, At, B0); G_BAR; G_SCHED;
;             G_STAGE(G_SB(0, 1), b2 + hstepB, voffB);
;             G_WAIT_V(6); G_BAR; G_MMA(1, 1, At, B1); G_BAR;
.LBB0_752:
	s_add_u32 s28, s2, 0xfffc0080
	s_addc_u32 s29, s3, -1
	s_add_i32 s68, 0, 0x10000
	v_add_u32_e32 v172, s68, v177
	ds_read_b128 v[128:131], v172
	ds_read_b128 v[168:171], v172 offset:1024
	ds_read_b128 v[180:183], v172 offset:2048
	ds_read_b128 v[184:187], v172 offset:3072
	s_cmp_eq_u32 s76, 12
	s_cselect_b32 s31, s27, s29
	s_cselect_b32 s30, s33, s28
	s_cselect_b32 s29, s38, s53
	s_cselect_b32 s28, s39, s51
	v_lshl_add_u64 v[172:173], s[2:3], 0, v[164:165]
	s_add_i32 m0, s36, 0xc000
	ds_read_b128 v[188:191], v178
	ds_read_b128 v[194:197], v178 offset:1024
	ds_read_b128 v[198:201], v178 offset:2048
	ds_read_b128 v[202:205], v178 offset:3072
	ds_read_b128 v[206:209], v178 offset:4096
	ds_read_b128 v[210:213], v178 offset:5120
	ds_read_b128 v[214:217], v178 offset:6144
	ds_read_b128 v[218:221], v178 offset:7168
	global_load_lds_dwordx4 v[172:173], off
	v_lshl_add_u64 v[172:173], s[2:3], 0, v[166:167]
	s_add_i32 m0, s36, 0xe000
	s_nop 0
	global_load_lds_dwordx4 v[172:173], off
	s_waitcnt lgkmcnt(8)
	s_barrier
	s_waitcnt lgkmcnt(0)
	s_setprio 1
	s_waitcnt lgkmcnt(0)
	v_mfma_f32_16x16x32_bf16 v[124:127], v[128:131], v[188:191], v[124:127]
	v_mfma_f32_16x16x32_bf16 v[120:123], v[180:183], v[188:191], v[120:123]
	v_mfma_f32_16x16x32_bf16 v[112:115], v[128:131], v[198:201], v[112:115]
	v_mfma_f32_16x16x32_bf16 v[104:107], v[180:183], v[198:201], v[104:107]
	v_mfma_f32_16x16x32_bf16 v[96:99], v[128:131], v[206:209], v[96:99]
	v_mfma_f32_16x16x32_bf16 v[88:91], v[180:183], v[206:209], v[88:91]
	v_mfma_f32_16x16x32_bf16 v[80:83], v[128:131], v[214:217], v[80:83]
	v_mfma_f32_16x16x32_bf16 v[72:75], v[180:183], v[214:217], v[72:75]
	v_mfma_f32_16x16x32_bf16 v[124:127], v[168:171], v[194:197], v[124:127]
	v_mfma_f32_16x16x32_bf16 v[120:123], v[184:187], v[194:197], v[120:123]
	v_mfma_f32_16x16x32_bf16 v[112:115], v[168:171], v[202:205], v[112:115]
	v_mfma_f32_16x16x32_bf16 v[104:107], v[184:187], v[202:205], v[104:107]
	v_mfma_f32_16x16x32_bf16 v[96:99], v[168:171], v[210:213], v[96:99]
	v_mfma_f32_16x16x32_bf16 v[88:91], v[184:187], v[210:213], v[88:91]
	v_mfma_f32_16x16x32_bf16 v[80:83], v[168:171], v[218:221], v[80:83]
	v_mfma_f32_16x16x32_bf16 v[72:75], v[184:187], v[218:221], v[72:75]
	s_setprio 0
	s_barrier
	s_add_i32 s77, 0, 0x14000
	v_add_u32_e32 v172, s77, v177
	s_add_i32 s68, s68, s35
	ds_read_b128 v[222:225], v172
	ds_read_b128 v[226:229], v172 offset:1024
	ds_read_b128 v[230:233], v172 offset:2048
	ds_read_b128 v[234:237], v172 offset:3072
	v_lshl_add_u64 v[172:173], s[28:29], 0, v[142:143]
	s_mov_b32 m0, s68
	v_lshl_add_u64 v[238:239], s[28:29], 0, v[138:139]
	global_load_lds_dwordx4 v[172:173], off
	s_add_i32 m0, s68, 0x2000
	s_nop 0
	global_load_lds_dwordx4 v[238:239], off
	s_barrier
	s_waitcnt lgkmcnt(0)
	s_setprio 1
	s_waitcnt lgkmcnt(0)
	v_mfma_f32_16x16x32_bf16 v[116:119], v[222:225], v[188:191], v[116:119]
	v_mfma_f32_16x16x32_bf16 v[108:111], v[230:233], v[188:191], v[108:111]
	v_mfma_f32_16x16x32_bf16 v[100:103], v[222:225], v[198:201], v[100:103]
	v_mfma_f32_16x16x32_bf16 v[92:95], v[230:233], v[198:201], v[92:95]
	v_mfma_f32_16x16x32_bf16 v[84:87], v[222:225], v[206:209], v[84:87]
	v_mfma_f32_16x16x32_bf16 v[76:79], v[230:233], v[206:209], v[76:79]
	v_mfma_f32_16x16x32_bf16 v[68:71], v[222:225], v[214:217], v[68:71]
	v_mfma_f32_16x16x32_bf16 v[64:67], v[230:233], v[214:217], v[64:67]
	v_mfma_f32_16x16x32_bf16 v[116:119], v[226:229], v[194:197], v[116:119]
	v_mfma_f32_16x16x32_bf16 v[108:111], v[234:237], v[194:197], v[108:111]
	v_mfma_f32_16x16x32_bf16 v[100:103], v[226:229], v[202:205], v[100:103]
	v_mfma_f32_16x16x32_bf16 v[92:95], v[234:237], v[202:205], v[92:95]
	v_mfma_f32_16x16x32_bf16 v[84:87], v[226:229], v[210:213], v[84:87]
	v_mfma_f32_16x16x32_bf16 v[76:79], v[234:237], v[210:213], v[76:79]
	v_mfma_f32_16x16x32_bf16 v[68:71], v[226:229], v[218:221], v[68:71]
	v_mfma_f32_16x16x32_bf16 v[64:67], v[234:237], v[218:221], v[64:67]
	s_setprio 0
	s_mov_b32 m0, s36
	v_lshl_add_u64 v[240:241], s[30:31], 0, v[144:145]
	s_barrier
	ds_read_b128 v[188:191], v178 offset:16384
	ds_read_b128 v[194:197], v178 offset:17408
	ds_read_b128 v[198:201], v178 offset:18432
	ds_read_b128 v[202:205], v178 offset:19456
	ds_read_b128 v[206:209], v178 offset:20480
	ds_read_b128 v[210:213], v178 offset:21504
	ds_read_b128 v[214:217], v178 offset:22528
	ds_read_b128 v[218:221], v178 offset:23552
	global_load_lds_dwordx4 v[240:241], off
	v_lshl_add_u64 v[242:243], s[30:31], 0, v[140:141]
	s_mov_b32 m0, s37
	s_nop 0
	global_load_lds_dwordx4 v[242:243], off
	s_barrier
	s_waitcnt lgkmcnt(0)
	s_setprio 1
	s_waitcnt lgkmcnt(0)
	v_mfma_f32_16x16x32_bf16 v[60:63], v[128:131], v[188:191], v[60:63]
	v_mfma_f32_16x16x32_bf16 v[56:59], v[180:183], v[188:191], v[56:59]
	v_mfma_f32_16x16x32_bf16 v[48:51], v[128:131], v[198:201], v[48:51]
	v_mfma_f32_16x16x32_bf16 v[40:43], v[180:183], v[198:201], v[40:43]
	v_mfma_f32_16x16x32_bf16 v[32:35], v[128:131], v[206:209], v[32:35]
	v_mfma_f32_16x16x32_bf16 v[24:27], v[180:183], v[206:209], v[24:27]
	v_mfma_f32_16x16x32_bf16 v[16:19], v[128:131], v[214:217], v[16:19]
	v_mfma_f32_16x16x32_bf16 v[8:11], v[180:183], v[214:217], v[8:11]
	v_mfma_f32_16x16x32_bf16 v[60:63], v[168:171], v[194:197], v[60:63]
	v_mfma_f32_16x16x32_bf16 v[56:59], v[184:187], v[194:197], v[56:59]
	v_mfma_f32_16x16x32_bf16 v[48:51], v[168:171], v[202:205], v[48:51]
	v_mfma_f32_16x16x32_bf16 v[40:43], v[184:187], v[202:205], v[40:43]
	v_mfma_f32_16x16x32_bf16 v[32:35], v[168:171], v[210:213], v[32:35]
	v_mfma_f32_16x16x32_bf16 v[24:27], v[184:187], v[210:213], v[24:27]
	v_mfma_f32_16x16x32_bf16 v[16:19], v[168:171], v[218:221], v[16:19]
	v_mfma_f32_16x16x32_bf16 v[8:11], v[184:187], v[218:221], v[8:11]
	s_setprio 0
	s_barrier
; #define G_STAGE(bufoff, gbase, voff) do { _Pragma("unroll") for (int _i = 0; _i < 2; ++_i) \
;         __builtin_amdgcn_global_load_lds((const unsigned*)((const char*)(gbase) + (voff)[_i]), (LAS unsigned*)(lds + (bufoff) + ldsw + _i * 8192), 16, 0, 0); } while (0)
; #define G_LDA(dst, b, h) do { _Pragma("unroll") for (int m = 0; m < 4; ++m) _Pragma("unroll") for (int k = 0; k < 2; ++k) dst[m][k] = *(const LAS bf16x8*)(lds + G_SA(b, h) + aoff + m * 2048 + k * 1024); } while (0)
; #define G_LDB(dst, b, h) do { _Pragma("unroll") for (int n = 0; n < 2; ++n) _Pragma("unroll") for (int k = 0; k < 2; ++k) dst[n][k] = *(const LAS bf16x8*)(lds + G_SB(b, h) + boff + n * 2048 + k * 1024); } while (0)
; #define G_MMA(ai, bj, At, Bt) do { __builtin_amdgcn_s_setprio(1); _Pragma("unroll") for (int m = 0; m < 4; ++m) _Pragma("unroll") for (int n = 0; n < 2; ++n) _Pragma("unroll") for (int k = 0; k < 2; ++k) \
;         acc[ai][bj][m][n] = __builtin_amdgcn_mfma_f32_16x16x32_bf16(Bt[n][k], At[m][k], acc[ai][bj][m][n], 0, 0, 0); __builtin_amdgcn_s_setprio(0); } while (0)
; #define G_WAIT_V(n) asm volatile("s_waitcnt vmcnt(" #n ")" ::: "memory")
; #define G_WAIT_L(n) asm volatile("s_waitcnt lgkmcnt(" #n ")" ::: "memory")
; #define G_BAR __builtin_amdgcn_s_barrier()
; #define G_SCHED __builtin_amdgcn_sched_barrier(0)
; template <bool PERM, class Dec, class Epi>
; DI void gemm_phase(LAS unsigned char* lds, const int nM, const int nN, const int K, const int lda, const int ldb, const Dec& dec, const Epi& epi, const int vb, const int panel = -1) {
;     ...
;             G_WAIT_V(6); G_BAR; G_MMA(1, 1, At, B1); G_BAR;
;             G_LDB(B0, 1, 0); G_SCHED; G_LDA(At, 1, 0); G_STAGE(G_SA(0, 1), a2 + hstepA, voffA);
;             G_WAIT_L(8); G_BAR; G_WAIT_L(0); G_MMA(0, 0, At, B0); G_BAR; G_SCHED;
;             G_LDB(B1, 1, 1); G_STAGE(G_SB(1, 0), b3, voffB);
;             G_BAR; G_WAIT_L(0); G_MMA(0, 1, At, B1); G_BAR;
;             G_LDA(At, 1, 1); G_STAGE(G_SA(1, 0), a3, voffA);
;             G_BAR; G_WAIT_L(0); G_MMA(1, 0, At, B0); G_BAR; G_SCHED;
	s_add_u32 s68, s28, 0x40000
	s_addc_u32 s69, s29, 0
	s_add_i32 s77, s77, s35
	v_lshl_add_u64 v[128:129], s[68:69], 0, v[142:143]
	s_mov_b32 m0, s77
	s_nop 0
	global_load_lds_dwordx4 v[128:129], off
	v_lshl_add_u64 v[128:129], s[68:69], 0, v[138:139]
	s_add_i32 m0, s77, 0x2000
	s_nop 0
	global_load_lds_dwordx4 v[128:129], off
	s_waitcnt vmcnt(6)
	s_barrier
	s_setprio 1
	v_mfma_f32_16x16x32_bf16 v[52:55], v[222:225], v[188:191], v[52:55]
	v_mfma_f32_16x16x32_bf16 v[44:47], v[230:233], v[188:191], v[44:47]
	v_mfma_f32_16x16x32_bf16 v[36:39], v[222:225], v[198:201], v[36:39]
	v_mfma_f32_16x16x32_bf16 v[28:31], v[230:233], v[198:201], v[28:31]
	v_mfma_f32_16x16x32_bf16 v[20:23], v[222:225], v[206:209], v[20:23]
	v_mfma_f32_16x16x32_bf16 v[12:15], v[230:233], v[206:209], v[12:15]
	v_mfma_f32_16x16x32_bf16 v[4:7], v[222:225], v[214:217], v[4:7]
	v_mfma_f32_16x16x32_bf16 v[0:3], v[230:233], v[214:217], v[0:3]
	v_mfma_f32_16x16x32_bf16 v[52:55], v[226:229], v[194:197], v[52:55]
	v_mfma_f32_16x16x32_bf16 v[44:47], v[234:237], v[194:197], v[44:47]
	v_mfma_f32_16x16x32_bf16 v[36:39], v[226:229], v[202:205], v[36:39]
	v_mfma_f32_16x16x32_bf16 v[28:31], v[234:237], v[202:205], v[28:31]
	v_mfma_f32_16x16x32_bf16 v[20:23], v[226:229], v[210:213], v[20:23]
	v_mfma_f32_16x16x32_bf16 v[12:15], v[234:237], v[210:213], v[12:15]
	v_mfma_f32_16x16x32_bf16 v[4:7], v[226:229], v[218:221], v[4:7]
	v_mfma_f32_16x16x32_bf16 v[0:3], v[234:237], v[218:221], v[0:3]
	s_setprio 0
	s_add_i32 s68, 0, 0x18000
	v_add_u32_e32 v179, s68, v177
	s_barrier
	ds_read_b128 v[128:131], v179
	ds_read_b128 v[168:171], v179 offset:1024
	ds_read_b128 v[180:183], v179 offset:2048
	ds_read_b128 v[184:187], v179 offset:3072
	s_add_u32 s30, s30, 0x40000
	s_addc_u32 s31, s31, 0
	s_mov_b32 m0, s70
	v_lshl_add_u64 v[222:223], s[30:31], 0, v[144:145]
	ds_read_b128 v[188:191], v178 offset:32768
	ds_read_b128 v[194:197], v178 offset:33792
	ds_read_b128 v[198:201], v178 offset:34816
	ds_read_b128 v[202:205], v178 offset:35840
	ds_read_b128 v[206:209], v178 offset:36864
	ds_read_b128 v[210:213], v178 offset:37888
	ds_read_b128 v[214:217], v178 offset:38912
	ds_read_b128 v[218:221], v178 offset:39936
	global_load_lds_dwordx4 v[222:223], off
	v_lshl_add_u64 v[222:223], s[30:31], 0, v[140:141]
	s_mov_b32 m0, s71
	s_nop 0
	global_load_lds_dwordx4 v[222:223], off
	s_waitcnt lgkmcnt(8)
	s_barrier
	s_waitcnt lgkmcnt(0)
	s_setprio 1
	s_waitcnt lgkmcnt(0)
	v_mfma_f32_16x16x32_bf16 v[124:127], v[128:131], v[188:191], v[124:127]
	v_mfma_f32_16x16x32_bf16 v[120:123], v[180:183], v[188:191], v[120:123]
	v_mfma_f32_16x16x32_bf16 v[112:115], v[128:131], v[198:201], v[112:115]
	v_mfma_f32_16x16x32_bf16 v[104:107], v[180:183], v[198:201], v[104:107]
	v_mfma_f32_16x16x32_bf16 v[96:99], v[128:131], v[206:209], v[96:99]
	v_mfma_f32_16x16x32_bf16 v[88:91], v[180:183], v[206:209], v[88:91]
	v_mfma_f32_16x16x32_bf16 v[80:83], v[128:131], v[214:217], v[80:83]
	v_mfma_f32_16x16x32_bf16 v[72:75], v[180:183], v[214:217], v[72:75]
	v_mfma_f32_16x16x32_bf16 v[124:127], v[168:171], v[194:197], v[124:127]
	v_mfma_f32_16x16x32_bf16 v[120:123], v[184:187], v[194:197], v[120:123]
	v_mfma_f32_16x16x32_bf16 v[112:115], v[168:171], v[202:205], v[112:115]
	v_mfma_f32_16x16x32_bf16 v[104:107], v[184:187], v[202:205], v[104:107]
	v_mfma_f32_16x16x32_bf16 v[96:99], v[168:171], v[210:213], v[96:99]
	v_mfma_f32_16x16x32_bf16 v[88:91], v[184:187], v[210:213], v[88:91]
	v_mfma_f32_16x16x32_bf16 v[80:83], v[168:171], v[218:221], v[80:83]
	v_mfma_f32_16x16x32_bf16 v[72:75], v[184:187], v[218:221], v[72:75]
	s_setprio 0
	s_barrier
	s_add_i32 s30, 0, 0x1c000
	s_add_i32 s31, s68, s35
	v_add_u32_e32 v179, s30, v177
	v_lshl_add_u64 v[172:173], v[172:173], 0, s[48:49]
	s_mov_b32 m0, s31
	ds_read_b128 v[222:225], v179
	ds_read_b128 v[226:229], v179 offset:1024
	ds_read_b128 v[230:233], v179 offset:2048
	ds_read_b128 v[234:237], v179 offset:3072
	global_load_lds_dwordx4 v[172:173], off
	v_lshl_add_u64 v[172:173], v[238:239], 0, s[48:49]
	s_add_i32 m0, s31, 0x2000
	s_nop 0
	global_load_lds_dwordx4 v[172:173], off
	s_barrier
	s_waitcnt lgkmcnt(0)
	s_setprio 1
	s_waitcnt lgkmcnt(0)
	v_mfma_f32_16x16x32_bf16 v[116:119], v[222:225], v[188:191], v[116:119]
	v_mfma_f32_16x16x32_bf16 v[108:111], v[230:233], v[188:191], v[108:111]
	v_mfma_f32_16x16x32_bf16 v[100:103], v[222:225], v[198:201], v[100:103]
	v_mfma_f32_16x16x32_bf16 v[92:95], v[230:233], v[198:201], v[92:95]
	v_mfma_f32_16x16x32_bf16 v[84:87], v[222:225], v[206:209], v[84:87]
	v_mfma_f32_16x16x32_bf16 v[76:79], v[230:233], v[206:209], v[76:79]
	v_mfma_f32_16x16x32_bf16 v[68:71], v[222:225], v[214:217], v[68:71]
	v_mfma_f32_16x16x32_bf16 v[64:67], v[230:233], v[214:217], v[64:67]
	v_mfma_f32_16x16x32_bf16 v[116:119], v[226:229], v[194:197], v[116:119]
	v_mfma_f32_16x16x32_bf16 v[108:111], v[234:237], v[194:197], v[108:111]
	v_mfma_f32_16x16x32_bf16 v[100:103], v[226:229], v[202:205], v[100:103]
	v_mfma_f32_16x16x32_bf16 v[92:95], v[234:237], v[202:205], v[92:95]
	v_mfma_f32_16x16x32_bf16 v[84:87], v[226:229], v[210:213], v[84:87]
	v_mfma_f32_16x16x32_bf16 v[76:79], v[234:237], v[210:213], v[76:79]
	v_mfma_f32_16x16x32_bf16 v[68:71], v[226:229], v[218:221], v[68:71]
	v_mfma_f32_16x16x32_bf16 v[64:67], v[234:237], v[218:221], v[64:67]
	s_setprio 0
	s_mov_b32 m0, s72
	v_lshl_add_u64 v[172:173], v[240:241], 0, s[48:49]
	s_barrier
	ds_read_b128 v[188:191], v178 offset:49152
	ds_read_b128 v[194:197], v178 offset:50176
	ds_read_b128 v[198:201], v178 offset:51200
	ds_read_b128 v[202:205], v178 offset:52224
	ds_read_b128 v[206:209], v178 offset:53248
	ds_read_b128 v[210:213], v178 offset:54272
	ds_read_b128 v[214:217], v178 offset:55296
	ds_read_b128 v[218:221], v178 offset:56320
	global_load_lds_dwordx4 v[172:173], off
	v_lshl_add_u64 v[172:173], v[242:243], 0, s[48:49]
	s_mov_b32 m0, s73
	s_nop 0
	global_load_lds_dwordx4 v[172:173], off
	s_barrier
; DI unsigned pk2(float a, float b) { f32x2 v = {a, b}; bf2_t r = __builtin_convertvector(v, bf2_t); return __builtin_bit_cast(unsigned, r); }
; DI float sigm(float x) { return __builtin_amdgcn_rcpf(1.f + __expf(-x)); }
; DI float silu_(float x) { return x * __builtin_amdgcn_rcpf(1.f + __expf(-x)); }
; #define G_STAGE(bufoff, gbase, voff) do { _Pragma("unroll") for (int _i = 0; _i < 2; ++_i) \
;         __builtin_amdgcn_global_load_lds((const unsigned*)((const char*)(gbase) + (voff)[_i]), (LAS unsigned*)(lds + (bufoff) + ldsw + _i * 8192), 16, 0, 0); } while (0)
; #define G_WAIT_V(n) asm volatile("s_waitcnt vmcnt(" #n ")" ::: "memory")
; #define G_WAIT_L(n) asm volatile("s_waitcnt lgkmcnt(" #n ")" ::: "memory")
; #define G_BAR __builtin_amdgcn_s_barrier()
; #define G_SCHED __builtin_amdgcn_sched_barrier(0)
; template <bool PERM, class Dec, class Epi>
; DI void gemm_phase(LAS unsigned char* lds, const int nM, const int nN, const int K, const int lda, const int ldb, const Dec& dec, const Epi& epi, const int vb, const int panel = -1) {
;     ...
;             G_BAR; G_WAIT_L(0); G_MMA(1, 0, At, B0); G_BAR; G_SCHED;
;             G_STAGE(G_SB(1, 1), b3 + hstepB, voffB);
;             G_WAIT_V(6); G_BAR; G_MMA(1, 1, At, B1); G_BAR;
;         }
; template <int ACT>
; DI void epi_bf16(const f32x4 (&acc)[2][2][4][2], bf16_t* O, const int ldc, int wr, int wc, int fr, int fq, const float* ssrow = nullptr) {
;     ...
;         for (int m = 0; m < 4; ++m) {
;             bf16_t* rowp = O + (size_t)(ai * HALF + wr * 64 + m * 16 + fr) * ldc + wc * 32 + 8 * fq;
;             const float rsc = ssrow ? __builtin_amdgcn_rsqf(ssrow[ai * HALF + wr * 64 + m * 16 + fr] * (1.f / 1024.f) + EPS_) : 1.f;
; #pragma unroll
;             for (int bj = 0; bj < 2; ++bj) {
;                 f32x4 v0 = acc[ai][bj][m][0] * rsc, v1 = acc[ai][bj][m][1] * rsc;
;                 if (ACT == 1) {
; #pragma unroll
;                     for (int j = 0; j < 4; ++j) { v0[j] = silu_(v0[j]); v1[j] = silu_(v1[j]); } }
;                 if (ACT == 2) {
; #pragma unroll
;                     for (int j = 0; j < 4; ++j) { v0[j] = sigm(v0[j]); v1[j] = sigm(v1[j]); } }
;                 u32x4 w; w[0] = pk2(v0[0], v0[1]); w[1] = pk2(v0[2], v0[3]); w[2] = pk2(v1[0], v1[1]); w[3] = pk2(v1[2], v1[3]);
;                 *(u32x4*)(rowp + bj * HALF) = w;
	s_waitcnt lgkmcnt(0)
	s_setprio 1
	s_waitcnt lgkmcnt(0)
	v_mfma_f32_16x16x32_bf16 v[60:63], v[128:131], v[188:191], v[60:63]
	v_mfma_f32_16x16x32_bf16 v[56:59], v[180:183], v[188:191], v[56:59]
	v_mfma_f32_16x16x32_bf16 v[48:51], v[128:131], v[198:201], v[48:51]
	v_mfma_f32_16x16x32_bf16 v[40:43], v[180:183], v[198:201], v[40:43]
	v_mfma_f32_16x16x32_bf16 v[32:35], v[128:131], v[206:209], v[32:35]
	v_mfma_f32_16x16x32_bf16 v[24:27], v[180:183], v[206:209], v[24:27]
	v_mfma_f32_16x16x32_bf16 v[16:19], v[128:131], v[214:217], v[16:19]
	v_mfma_f32_16x16x32_bf16 v[8:11], v[180:183], v[214:217], v[8:11]
	v_mfma_f32_16x16x32_bf16 v[60:63], v[168:171], v[194:197], v[60:63]
	v_mfma_f32_16x16x32_bf16 v[56:59], v[184:187], v[194:197], v[56:59]
	v_mfma_f32_16x16x32_bf16 v[48:51], v[168:171], v[202:205], v[48:51]
	v_mfma_f32_16x16x32_bf16 v[40:43], v[184:187], v[202:205], v[40:43]
	v_mfma_f32_16x16x32_bf16 v[32:35], v[168:171], v[210:213], v[32:35]
	v_mfma_f32_16x16x32_bf16 v[24:27], v[184:187], v[210:213], v[24:27]
	v_mfma_f32_16x16x32_bf16 v[16:19], v[168:171], v[218:221], v[16:19]
	v_mfma_f32_16x16x32_bf16 v[8:11], v[184:187], v[218:221], v[8:11]
	s_setprio 0
	s_barrier
	s_add_u32 s28, s28, 0x40080
	s_addc_u32 s29, s29, 0
	s_add_i32 s30, s30, s35
	v_lshl_add_u64 v[128:129], s[28:29], 0, v[142:143]
	s_mov_b32 m0, s30
	s_nop 0
	global_load_lds_dwordx4 v[128:129], off
	v_lshl_add_u64 v[128:129], s[28:29], 0, v[138:139]
	s_add_i32 m0, s30, 0x2000
	s_nop 0
	global_load_lds_dwordx4 v[128:129], off
	s_waitcnt vmcnt(6)
	s_barrier
	s_setprio 1
	v_mfma_f32_16x16x32_bf16 v[52:55], v[222:225], v[188:191], v[52:55]
	v_mfma_f32_16x16x32_bf16 v[44:47], v[230:233], v[188:191], v[44:47]
	v_mfma_f32_16x16x32_bf16 v[36:39], v[222:225], v[198:201], v[36:39]
	v_mfma_f32_16x16x32_bf16 v[28:31], v[230:233], v[198:201], v[28:31]
	v_mfma_f32_16x16x32_bf16 v[20:23], v[222:225], v[206:209], v[20:23]
	v_mfma_f32_16x16x32_bf16 v[12:15], v[230:233], v[206:209], v[12:15]
	v_mfma_f32_16x16x32_bf16 v[4:7], v[222:225], v[214:217], v[4:7]
	v_mfma_f32_16x16x32_bf16 v[0:3], v[230:233], v[214:217], v[0:3]
	v_mfma_f32_16x16x32_bf16 v[52:55], v[226:229], v[194:197], v[52:55]
	v_mfma_f32_16x16x32_bf16 v[44:47], v[234:237], v[194:197], v[44:47]
	v_mfma_f32_16x16x32_bf16 v[36:39], v[226:229], v[202:205], v[36:39]
	v_mfma_f32_16x16x32_bf16 v[28:31], v[234:237], v[202:205], v[28:31]
	v_mfma_f32_16x16x32_bf16 v[20:23], v[226:229], v[210:213], v[20:23]
	v_mfma_f32_16x16x32_bf16 v[12:15], v[234:237], v[210:213], v[12:15]
	v_mfma_f32_16x16x32_bf16 v[4:7], v[226:229], v[218:221], v[4:7]
	v_mfma_f32_16x16x32_bf16 v[0:3], v[234:237], v[218:221], v[0:3]
	s_setprio 0
	s_add_i32 s76, s76, 2
	s_add_u32 s2, s2, 0x100
	s_addc_u32 s3, s3, 0
	s_add_u32 s51, s51, 0x100
	s_addc_u32 s53, s53, 0
	s_cmp_gt_u32 s76, 13
	s_barrier
	s_cbranch_scc0 .LBB0_752
	s_lshl_b32 s2, s4, 8
	s_ashr_i32 s3, s2, 31
	s_lshl_b64 s[2:3], s[2:3], 2
	s_add_u32 s28, s86, s2
	s_addc_u32 s29, s87, s3
	s_lshl_b32 s30, s15, 8
	s_cmp_gt_i32 s15, 5
	s_mul_hi_i32 s15, s4, 0xc0000
	s_mul_i32 s27, s4, 0xc0000
	s_mov_b64 s[2:3], -1
	v_lshl_add_u64 v[168:169], v[146:147], 2, s[28:29]
	s_cbranch_scc0 .LBB0_755
	global_load_dword v236, v[168:169], off
	global_load_dword v237, v[168:169], off offset:64
	global_load_dword v238, v[168:169], off offset:128
	global_load_dword v239, v[168:169], off offset:192
	global_load_dword v240, v[168:169], off offset:512
	global_load_dword v241, v[168:169], off offset:576
	global_load_dword v242, v[168:169], off offset:640
	global_load_dword v243, v[168:169], off offset:704
	s_add_u32 s28, s16, s27
	s_addc_u32 s29, s17, s15
	s_add_i32 s4, s30, 0xfffffa00
	s_lshl_b64 s[2:3], s[4:5], 1
	s_add_u32 s28, s28, s2
	s_addc_u32 s29, s29, s3
	s_lshl_b32 s2, s74, 1
	s_add_u32 s2, s28, s2
	s_addc_u32 s3, s29, 0
	v_lshl_add_u64 v[128:129], s[2:3], 0, v[132:133]
	v_lshl_add_u64 v[130:131], v[128:129], 0, v[148:149]
	s_mov_b64 s[2:3], 0
	s_waitcnt vmcnt(0)
	v_mov_b32_e32 v170, v236
	v_fmamk_f32 v170, v170, 0x3a800000, v175
	v_rsq_f32_e32 v180, v170
	s_nop 0
	v_pk_mul_f32 v[172:173], v[124:125], v[180:181] op_sel_hi:[1,0]
	s_nop 0
	v_mul_f32_e32 v179, 0xbfb8aa3b, v172
	v_exp_f32_e32 v179, v179
	v_pk_mul_f32 v[184:185], v[120:121], v[180:181] op_sel_hi:[1,0]
	v_pk_mul_f32 v[170:171], v[126:127], v[180:181] op_sel_hi:[1,0]
	v_pk_mul_f32 v[182:183], v[122:123], v[180:181] op_sel_hi:[1,0]
	v_add_f32_e32 v179, 1.0, v179
	v_rcp_f32_e32 v186, v179
	v_mul_f32_e32 v179, 0xbfb8aa3b, v184
	v_exp_f32_e32 v179, v179
	s_nop 0
	v_add_f32_e32 v179, 1.0, v179
	v_rcp_f32_e32 v188, v179
	v_mul_f32_e32 v179, 0xbfb8aa3b, v173
	v_exp_f32_e32 v179, v179
	s_nop 0
	v_add_f32_e32 v179, 1.0, v179
	v_rcp_f32_e32 v187, v179
	v_mul_f32_e32 v179, 0xbfb8aa3b, v185
	v_exp_f32_e32 v179, v179
	v_pk_mul_f32 v[172:173], v[172:173], v[186:187]
	v_add_f32_e32 v179, 1.0, v179
	v_rcp_f32_e32 v189, v179
	v_mul_f32_e32 v179, 0xbfb8aa3b, v170
	v_exp_f32_e32 v179, v179
	v_pk_mul_f32 v[184:185], v[184:185], v[188:189]
	v_add_f32_e32 v179, 1.0, v179
	v_rcp_f32_e32 v186, v179
	v_mul_f32_e32 v179, 0xbfb8aa3b, v182
	v_exp_f32_e32 v179, v179
	s_nop 0
	v_add_f32_e32 v179, 1.0, v179
	v_rcp_f32_e32 v188, v179
	v_mul_f32_e32 v179, 0xbfb8aa3b, v171
	v_exp_f32_e32 v179, v179
	s_nop 0
	v_add_f32_e32 v179, 1.0, v179
	v_rcp_f32_e32 v187, v179
	s_nop 0
	v_pk_mul_f32 v[186:187], v[170:171], v[186:187]
	v_mul_f32_e32 v170, 0xbfb8aa3b, v183
	v_exp_f32_e32 v170, v170
	v_cvt_pk_bf16_f32 v171, v186, v187
	v_add_f32_e32 v170, 1.0, v170
	v_rcp_f32_e32 v189, v170
	v_cvt_pk_bf16_f32 v170, v172, v173
	v_cvt_pk_bf16_f32 v172, v184, v185
	v_pk_mul_f32 v[182:183], v[182:183], v[188:189]
	s_nop 0
	v_cvt_pk_bf16_f32 v173, v182, v183
	ds_bpermute_b32 v170, v193, v170
	ds_bpermute_b32 v171, v193, v171
	ds_bpermute_b32 v172, v193, v172
	ds_bpermute_b32 v173, v193, v173
	s_waitcnt lgkmcnt(0)
; DI unsigned pk2(float a, float b) { f32x2 v = {a, b}; bf2_t r = __builtin_convertvector(v, bf2_t); return __builtin_bit_cast(unsigned, r); }
; DI float sigm(float x) { return __builtin_amdgcn_rcpf(1.f + __expf(-x)); }
; DI float silu_(float x) { return x * __builtin_amdgcn_rcpf(1.f + __expf(-x)); }
; template <int ACT>
; DI void epi_bf16(const f32x4 (&acc)[2][2][4][2], bf16_t* O, const int ldc, int wr, int wc, int fr, int fq, const float* ssrow = nullptr) {
;     ...
;         for (int m = 0; m < 4; ++m) {
;             bf16_t* rowp = O + (size_t)(ai * HALF + wr * 64 + m * 16 + fr) * ldc + wc * 32 + 8 * fq;
;             const float rsc = ssrow ? __builtin_amdgcn_rsqf(ssrow[ai * HALF + wr * 64 + m * 16 + fr] * (1.f / 1024.f) + EPS_) : 1.f;
; #pragma unroll
;             for (int bj = 0; bj < 2; ++bj) {
;                 f32x4 v0 = acc[ai][bj][m][0] * rsc, v1 = acc[ai][bj][m][1] * rsc;
;                 if (ACT == 1) {
; #pragma unroll
;                     for (int j = 0; j < 4; ++j) { v0[j] = silu_(v0[j]); v1[j] = silu_(v1[j]); } }
;                 if (ACT == 2) {
; #pragma unroll
;                     for (int j = 0; j < 4; ++j) { v0[j] = sigm(v0[j]); v1[j] = sigm(v1[j]); } }
;                 u32x4 w; w[0] = pk2(v0[0], v0[1]); w[1] = pk2(v0[2], v0[3]); w[2] = pk2(v1[0], v1[1]); w[3] = pk2(v1[2], v1[3]);
;                 *(u32x4*)(rowp + bj * HALF) = w;
	global_store_dwordx4 v[130:131], v[170:173], off
	v_pk_mul_f32 v[182:183], v[118:119], v[180:181] op_sel_hi:[1,0]
	s_nop 0
	v_pk_mul_f32 v[172:173], v[116:117], v[180:181] op_sel_hi:[1,0]
	v_pk_mul_f32 v[170:171], v[110:111], v[180:181] op_sel_hi:[1,0]
	v_mul_f32_e32 v179, 0xbfb8aa3b, v172
	v_exp_f32_e32 v179, v179
	v_pk_mul_f32 v[180:181], v[108:109], v[180:181] op_sel_hi:[1,0]
	v_add_f32_e32 v179, 1.0, v179
	v_rcp_f32_e32 v184, v179
	v_mul_f32_e32 v179, 0xbfb8aa3b, v180
	v_exp_f32_e32 v179, v179
	s_nop 0
	v_add_f32_e32 v179, 1.0, v179
	v_rcp_f32_e32 v186, v179
	v_mul_f32_e32 v179, 0xbfb8aa3b, v173
	v_exp_f32_e32 v179, v179
	s_nop 0
	v_add_f32_e32 v179, 1.0, v179
	v_rcp_f32_e32 v185, v179
	v_mul_f32_e32 v179, 0xbfb8aa3b, v181
	v_exp_f32_e32 v179, v179
	v_pk_mul_f32 v[172:173], v[172:173], v[184:185]
	v_add_f32_e32 v179, 1.0, v179
	v_rcp_f32_e32 v187, v179
	v_mul_f32_e32 v179, 0xbfb8aa3b, v182
	v_exp_f32_e32 v179, v179
	v_pk_mul_f32 v[180:181], v[180:181], v[186:187]
	v_add_f32_e32 v179, 1.0, v179
	v_rcp_f32_e32 v184, v179
	v_mul_f32_e32 v179, 0xbfb8aa3b, v170
	v_exp_f32_e32 v179, v179
	s_nop 0
	v_add_f32_e32 v179, 1.0, v179
	v_rcp_f32_e32 v186, v179
	v_mul_f32_e32 v179, 0xbfb8aa3b, v183
	v_exp_f32_e32 v179, v179
	s_nop 0
	v_add_f32_e32 v179, 1.0, v179
	v_rcp_f32_e32 v185, v179
	v_mul_f32_e32 v179, 0xbfb8aa3b, v171
	v_exp_f32_e32 v179, v179
	v_pk_mul_f32 v[182:183], v[182:183], v[184:185]
	v_add_f32_e32 v179, 1.0, v179
	v_rcp_f32_e32 v187, v179
	s_nop 0
	v_pk_mul_f32 v[184:185], v[170:171], v[186:187]
	v_cvt_pk_bf16_f32 v170, v172, v173
	v_cvt_pk_bf16_f32 v171, v182, v183
	v_cvt_pk_bf16_f32 v172, v180, v181
	v_cvt_pk_bf16_f32 v173, v184, v185
	ds_bpermute_b32 v170, v193, v170
	ds_bpermute_b32 v171, v193, v171
	ds_bpermute_b32 v172, v193, v172
	ds_bpermute_b32 v173, v193, v173
	s_waitcnt lgkmcnt(0)
	global_store_dwordx4 v[130:131], v[170:173], off offset:256
	v_lshl_add_u64 v[130:131], v[128:129], 0, v[150:151]
	s_nop 1
	v_mov_b32_e32 v170, v237
	v_fmamk_f32 v170, v170, 0x3a800000, v175
	v_rsq_f32_e32 v180, v170
	s_nop 0
	v_pk_mul_f32 v[172:173], v[112:113], v[180:181] op_sel_hi:[1,0]
	s_nop 0
	v_mul_f32_e32 v179, 0xbfb8aa3b, v172
	v_exp_f32_e32 v179, v179
	v_pk_mul_f32 v[184:185], v[104:105], v[180:181] op_sel_hi:[1,0]
	v_pk_mul_f32 v[170:171], v[114:115], v[180:181] op_sel_hi:[1,0]
	v_pk_mul_f32 v[182:183], v[106:107], v[180:181] op_sel_hi:[1,0]
	v_add_f32_e32 v179, 1.0, v179
	v_rcp_f32_e32 v186, v179
	v_mul_f32_e32 v179, 0xbfb8aa3b, v184
	v_exp_f32_e32 v179, v179
	s_nop 0
	v_add_f32_e32 v179, 1.0, v179
	v_rcp_f32_e32 v188, v179
	v_mul_f32_e32 v179, 0xbfb8aa3b, v173
	v_exp_f32_e32 v179, v179
	s_nop 0
	v_add_f32_e32 v179, 1.0, v179
	v_rcp_f32_e32 v187, v179
	v_mul_f32_e32 v179, 0xbfb8aa3b, v185
	v_exp_f32_e32 v179, v179
	v_pk_mul_f32 v[172:173], v[172:173], v[186:187]
	v_add_f32_e32 v179, 1.0, v179
	v_rcp_f32_e32 v189, v179
	v_mul_f32_e32 v179, 0xbfb8aa3b, v170
	v_exp_f32_e32 v179, v179
	v_pk_mul_f32 v[184:185], v[184:185], v[188:189]
	v_add_f32_e32 v179, 1.0, v179
	v_rcp_f32_e32 v186, v179
	v_mul_f32_e32 v179, 0xbfb8aa3b, v182
	v_exp_f32_e32 v179, v179
	s_nop 0
	v_add_f32_e32 v179, 1.0, v179
	v_rcp_f32_e32 v188, v179
	v_mul_f32_e32 v179, 0xbfb8aa3b, v171
	v_exp_f32_e32 v179, v179
	s_nop 0
	v_add_f32_e32 v179, 1.0, v179
	v_rcp_f32_e32 v187, v179
	s_nop 0
	v_pk_mul_f32 v[186:187], v[170:171], v[186:187]
	v_mul_f32_e32 v170, 0xbfb8aa3b, v183
	v_exp_f32_e32 v170, v170
	v_cvt_pk_bf16_f32 v171, v186, v187
	v_add_f32_e32 v170, 1.0, v170
	v_rcp_f32_e32 v189, v170
	v_cvt_pk_bf16_f32 v170, v172, v173
	v_cvt_pk_bf16_f32 v172, v184, v185
	v_pk_mul_f32 v[182:183], v[182:183], v[188:189]
	s_nop 0
	v_cvt_pk_bf16_f32 v173, v182, v183
	ds_bpermute_b32 v170, v193, v170
	ds_bpermute_b32 v171, v193, v171
	ds_bpermute_b32 v172, v193, v172
	ds_bpermute_b32 v173, v193, v173
	s_waitcnt lgkmcnt(0)
	global_store_dwordx4 v[130:131], v[170:173], off
	v_pk_mul_f32 v[182:183], v[102:103], v[180:181] op_sel_hi:[1,0]
	s_nop 0
	v_pk_mul_f32 v[172:173], v[100:101], v[180:181] op_sel_hi:[1,0]
	v_pk_mul_f32 v[170:171], v[94:95], v[180:181] op_sel_hi:[1,0]
	v_mul_f32_e32 v179, 0xbfb8aa3b, v172
	v_exp_f32_e32 v179, v179
	v_pk_mul_f32 v[180:181], v[92:93], v[180:181] op_sel_hi:[1,0]
	v_add_f32_e32 v179, 1.0, v179
	v_rcp_f32_e32 v184, v179
	v_mul_f32_e32 v179, 0xbfb8aa3b, v180
	v_exp_f32_e32 v179, v179
	s_nop 0
	v_add_f32_e32 v179, 1.0, v179
	v_rcp_f32_e32 v186, v179
	v_mul_f32_e32 v179, 0xbfb8aa3b, v173
	v_exp_f32_e32 v179, v179
	s_nop 0
	v_add_f32_e32 v179, 1.0, v179
	v_rcp_f32_e32 v185, v179
	v_mul_f32_e32 v179, 0xbfb8aa3b, v181
	v_exp_f32_e32 v179, v179
	v_pk_mul_f32 v[172:173], v[172:173], v[184:185]
	v_add_f32_e32 v179, 1.0, v179
	v_rcp_f32_e32 v187, v179
	v_mul_f32_e32 v179, 0xbfb8aa3b, v182
	v_exp_f32_e32 v179, v179
	v_pk_mul_f32 v[180:181], v[180:181], v[186:187]
	v_add_f32_e32 v179, 1.0, v179
	v_rcp_f32_e32 v184, v179
	v_mul_f32_e32 v179, 0xbfb8aa3b, v170
	v_exp_f32_e32 v179, v179
	s_nop 0
	v_add_f32_e32 v179, 1.0, v179
	v_rcp_f32_e32 v186, v179
	v_mul_f32_e32 v179, 0xbfb8aa3b, v183
	v_exp_f32_e32 v179, v179
	s_nop 0
	v_add_f32_e32 v179, 1.0, v179
	v_rcp_f32_e32 v185, v179
	v_mul_f32_e32 v179, 0xbfb8aa3b, v171
	v_exp_f32_e32 v179, v179
	v_pk_mul_f32 v[182:183], v[182:183], v[184:185]
	v_add_f32_e32 v179, 1.0, v179
	v_rcp_f32_e32 v187, v179
	s_nop 0
	v_pk_mul_f32 v[184:185], v[170:171], v[186:187]
	v_cvt_pk_bf16_f32 v170, v172, v173
	v_cvt_pk_bf16_f32 v171, v182, v183
	v_cvt_pk_bf16_f32 v172, v180, v181
	v_cvt_pk_bf16_f32 v173, v184, v185
	ds_bpermute_b32 v170, v193, v170
	ds_bpermute_b32 v171, v193, v171
	ds_bpermute_b32 v172, v193, v172
	ds_bpermute_b32 v173, v193, v173
	s_waitcnt lgkmcnt(0)
; DI unsigned pk2(float a, float b) { f32x2 v = {a, b}; bf2_t r = __builtin_convertvector(v, bf2_t); return __builtin_bit_cast(unsigned, r); }
; DI float sigm(float x) { return __builtin_amdgcn_rcpf(1.f + __expf(-x)); }
; DI float silu_(float x) { return x * __builtin_amdgcn_rcpf(1.f + __expf(-x)); }
; template <int ACT>
; DI void epi_bf16(const f32x4 (&acc)[2][2][4][2], bf16_t* O, const int ldc, int wr, int wc, int fr, int fq, const float* ssrow = nullptr) {
;     ...
;         for (int m = 0; m < 4; ++m) {
;             bf16_t* rowp = O + (size_t)(ai * HALF + wr * 64 + m * 16 + fr) * ldc + wc * 32 + 8 * fq;
;             const float rsc = ssrow ? __builtin_amdgcn_rsqf(ssrow[ai * HALF + wr * 64 + m * 16 + fr] * (1.f / 1024.f) + EPS_) : 1.f;
; #pragma unroll
;             for (int bj = 0; bj < 2; ++bj) {
;                 f32x4 v0 = acc[ai][bj][m][0] * rsc, v1 = acc[ai][bj][m][1] * rsc;
;                 if (ACT == 1) {
; #pragma unroll
;                     for (int j = 0; j < 4; ++j) { v0[j] = silu_(v0[j]); v1[j] = silu_(v1[j]); } }
;                 if (ACT == 2) {
; #pragma unroll
;                     for (int j = 0; j < 4; ++j) { v0[j] = sigm(v0[j]); v1[j] = sigm(v1[j]); } }
;                 u32x4 w; w[0] = pk2(v0[0], v0[1]); w[1] = pk2(v0[2], v0[3]); w[2] = pk2(v1[0], v1[1]); w[3] = pk2(v1[2], v1[3]);
;                 *(u32x4*)(rowp + bj * HALF) = w;
	global_store_dwordx4 v[130:131], v[170:173], off offset:256
	v_lshl_add_u64 v[130:131], v[128:129], 0, v[152:153]
	s_nop 1
	v_mov_b32_e32 v170, v238
	v_fmamk_f32 v170, v170, 0x3a800000, v175
	v_rsq_f32_e32 v180, v170
	s_nop 0
	v_pk_mul_f32 v[172:173], v[96:97], v[180:181] op_sel_hi:[1,0]
	s_nop 0
	v_mul_f32_e32 v179, 0xbfb8aa3b, v172
	v_exp_f32_e32 v179, v179
	v_pk_mul_f32 v[184:185], v[88:89], v[180:181] op_sel_hi:[1,0]
	v_pk_mul_f32 v[170:171], v[98:99], v[180:181] op_sel_hi:[1,0]
	v_pk_mul_f32 v[182:183], v[90:91], v[180:181] op_sel_hi:[1,0]
	v_add_f32_e32 v179, 1.0, v179
	v_rcp_f32_e32 v186, v179
	v_mul_f32_e32 v179, 0xbfb8aa3b, v184
	v_exp_f32_e32 v179, v179
	s_nop 0
	v_add_f32_e32 v179, 1.0, v179
	v_rcp_f32_e32 v188, v179
	v_mul_f32_e32 v179, 0xbfb8aa3b, v173
	v_exp_f32_e32 v179, v179
	s_nop 0
	v_add_f32_e32 v179, 1.0, v179
	v_rcp_f32_e32 v187, v179
	v_mul_f32_e32 v179, 0xbfb8aa3b, v185
	v_exp_f32_e32 v179, v179
	v_pk_mul_f32 v[172:173], v[172:173], v[186:187]
	v_add_f32_e32 v179, 1.0, v179
	v_rcp_f32_e32 v189, v179
	v_mul_f32_e32 v179, 0xbfb8aa3b, v170
	v_exp_f32_e32 v179, v179
	v_pk_mul_f32 v[184:185], v[184:185], v[188:189]
	v_add_f32_e32 v179, 1.0, v179
	v_rcp_f32_e32 v186, v179
	v_mul_f32_e32 v179, 0xbfb8aa3b, v182
	v_exp_f32_e32 v179, v179
	s_nop 0
	v_add_f32_e32 v179, 1.0, v179
	v_rcp_f32_e32 v188, v179
	v_mul_f32_e32 v179, 0xbfb8aa3b, v171
	v_exp_f32_e32 v179, v179
	s_nop 0
	v_add_f32_e32 v179, 1.0, v179
	v_rcp_f32_e32 v187, v179
	s_nop 0
	v_pk_mul_f32 v[186:187], v[170:171], v[186:187]
	v_mul_f32_e32 v170, 0xbfb8aa3b, v183
	v_exp_f32_e32 v170, v170
	v_cvt_pk_bf16_f32 v171, v186, v187
	v_add_f32_e32 v170, 1.0, v170
	v_rcp_f32_e32 v189, v170
	v_cvt_pk_bf16_f32 v170, v172, v173
	v_cvt_pk_bf16_f32 v172, v184, v185
	v_pk_mul_f32 v[182:183], v[182:183], v[188:189]
	s_nop 0
	v_cvt_pk_bf16_f32 v173, v182, v183
	ds_bpermute_b32 v170, v193, v170
	ds_bpermute_b32 v171, v193, v171
	ds_bpermute_b32 v172, v193, v172
	ds_bpermute_b32 v173, v193, v173
	s_waitcnt lgkmcnt(0)
	global_store_dwordx4 v[130:131], v[170:173], off
	v_pk_mul_f32 v[182:183], v[86:87], v[180:181] op_sel_hi:[1,0]
	s_nop 0
	v_pk_mul_f32 v[172:173], v[84:85], v[180:181] op_sel_hi:[1,0]
	v_pk_mul_f32 v[170:171], v[78:79], v[180:181] op_sel_hi:[1,0]
	v_mul_f32_e32 v179, 0xbfb8aa3b, v172
	v_exp_f32_e32 v179, v179
	v_pk_mul_f32 v[180:181], v[76:77], v[180:181] op_sel_hi:[1,0]
	v_add_f32_e32 v179, 1.0, v179
	v_rcp_f32_e32 v184, v179
	v_mul_f32_e32 v179, 0xbfb8aa3b, v180
	v_exp_f32_e32 v179, v179
	s_nop 0
	v_add_f32_e32 v179, 1.0, v179
	v_rcp_f32_e32 v186, v179
	v_mul_f32_e32 v179, 0xbfb8aa3b, v173
	v_exp_f32_e32 v179, v179
	s_nop 0
	v_add_f32_e32 v179, 1.0, v179
	v_rcp_f32_e32 v185, v179
	v_mul_f32_e32 v179, 0xbfb8aa3b, v181
	v_exp_f32_e32 v179, v179
	v_pk_mul_f32 v[172:173], v[172:173], v[184:185]
	v_add_f32_e32 v179, 1.0, v179
	v_rcp_f32_e32 v187, v179
	v_mul_f32_e32 v179, 0xbfb8aa3b, v182
	v_exp_f32_e32 v179, v179
	v_pk_mul_f32 v[180:181], v[180:181], v[186:187]
	v_add_f32_e32 v179, 1.0, v179
	v_rcp_f32_e32 v184, v179
	v_mul_f32_e32 v179, 0xbfb8aa3b, v170
	v_exp_f32_e32 v179, v179
	s_nop 0
	v_add_f32_e32 v179, 1.0, v179
	v_rcp_f32_e32 v186, v179
	v_mul_f32_e32 v179, 0xbfb8aa3b, v183
	v_exp_f32_e32 v179, v179
	s_nop 0
	v_add_f32_e32 v179, 1.0, v179
	v_rcp_f32_e32 v185, v179
	v_mul_f32_e32 v179, 0xbfb8aa3b, v171
	v_exp_f32_e32 v179, v179
	v_pk_mul_f32 v[182:183], v[182:183], v[184:185]
	v_add_f32_e32 v179, 1.0, v179
	v_rcp_f32_e32 v187, v179
	s_nop 0
	v_pk_mul_f32 v[184:185], v[170:171], v[186:187]
	v_cvt_pk_bf16_f32 v170, v172, v173
	v_cvt_pk_bf16_f32 v171, v182, v183
	v_cvt_pk_bf16_f32 v172, v180, v181
	v_cvt_pk_bf16_f32 v173, v184, v185
	ds_bpermute_b32 v170, v193, v170
	ds_bpermute_b32 v171, v193, v171
	ds_bpermute_b32 v172, v193, v172
	ds_bpermute_b32 v173, v193, v173
	s_waitcnt lgkmcnt(0)
	global_store_dwordx4 v[130:131], v[170:173], off offset:256
	v_lshl_add_u64 v[130:131], v[128:129], 0, v[154:155]
	s_nop 1
	v_mov_b32_e32 v170, v239
	v_fmamk_f32 v170, v170, 0x3a800000, v175
	v_rsq_f32_e32 v180, v170
	s_nop 0
	v_pk_mul_f32 v[172:173], v[80:81], v[180:181] op_sel_hi:[1,0]
	s_nop 0
	v_mul_f32_e32 v179, 0xbfb8aa3b, v172
	v_exp_f32_e32 v179, v179
	v_pk_mul_f32 v[184:185], v[72:73], v[180:181] op_sel_hi:[1,0]
	v_pk_mul_f32 v[170:171], v[82:83], v[180:181] op_sel_hi:[1,0]
	v_pk_mul_f32 v[182:183], v[74:75], v[180:181] op_sel_hi:[1,0]
	v_add_f32_e32 v179, 1.0, v179
	v_rcp_f32_e32 v186, v179
	v_mul_f32_e32 v179, 0xbfb8aa3b, v184
	v_exp_f32_e32 v179, v179
	s_nop 0
	v_add_f32_e32 v179, 1.0, v179
	v_rcp_f32_e32 v188, v179
	v_mul_f32_e32 v179, 0xbfb8aa3b, v173
	v_exp_f32_e32 v179, v179
	s_nop 0
	v_add_f32_e32 v179, 1.0, v179
	v_rcp_f32_e32 v187, v179
	v_mul_f32_e32 v179, 0xbfb8aa3b, v185
	v_exp_f32_e32 v179, v179
	v_pk_mul_f32 v[172:173], v[172:173], v[186:187]
	v_add_f32_e32 v179, 1.0, v179
	v_rcp_f32_e32 v189, v179
	v_mul_f32_e32 v179, 0xbfb8aa3b, v170
	v_exp_f32_e32 v179, v179
	v_pk_mul_f32 v[184:185], v[184:185], v[188:189]
	v_add_f32_e32 v179, 1.0, v179
	v_rcp_f32_e32 v186, v179
	v_mul_f32_e32 v179, 0xbfb8aa3b, v182
	v_exp_f32_e32 v179, v179
	s_nop 0
	v_add_f32_e32 v179, 1.0, v179
	v_rcp_f32_e32 v188, v179
	v_mul_f32_e32 v179, 0xbfb8aa3b, v171
	v_exp_f32_e32 v179, v179
	s_nop 0
	v_add_f32_e32 v179, 1.0, v179
	v_rcp_f32_e32 v187, v179
	s_nop 0
	v_pk_mul_f32 v[186:187], v[170:171], v[186:187]
	v_mul_f32_e32 v170, 0xbfb8aa3b, v183
	v_exp_f32_e32 v170, v170
	v_cvt_pk_bf16_f32 v171, v186, v187
	v_add_f32_e32 v170, 1.0, v170
	v_rcp_f32_e32 v189, v170
	v_cvt_pk_bf16_f32 v170, v172, v173
	v_cvt_pk_bf16_f32 v172, v184, v185
	v_pk_mul_f32 v[182:183], v[182:183], v[188:189]
	s_nop 0
	v_cvt_pk_bf16_f32 v173, v182, v183
	ds_bpermute_b32 v170, v193, v170
	ds_bpermute_b32 v171, v193, v171
	ds_bpermute_b32 v172, v193, v172
	ds_bpermute_b32 v173, v193, v173
	s_waitcnt lgkmcnt(0)
; DI unsigned pk2(float a, float b) { f32x2 v = {a, b}; bf2_t r = __builtin_convertvector(v, bf2_t); return __builtin_bit_cast(unsigned, r); }
; DI float sigm(float x) { return __builtin_amdgcn_rcpf(1.f + __expf(-x)); }
; DI float silu_(float x) { return x * __builtin_amdgcn_rcpf(1.f + __expf(-x)); }
; template <int ACT>
; DI void epi_bf16(const f32x4 (&acc)[2][2][4][2], bf16_t* O, const int ldc, int wr, int wc, int fr, int fq, const float* ssrow = nullptr) {
;     ...
;         for (int m = 0; m < 4; ++m) {
;             bf16_t* rowp = O + (size_t)(ai * HALF + wr * 64 + m * 16 + fr) * ldc + wc * 32 + 8 * fq;
;             const float rsc = ssrow ? __builtin_amdgcn_rsqf(ssrow[ai * HALF + wr * 64 + m * 16 + fr] * (1.f / 1024.f) + EPS_) : 1.f;
; #pragma unroll
;             for (int bj = 0; bj < 2; ++bj) {
;                 f32x4 v0 = acc[ai][bj][m][0] * rsc, v1 = acc[ai][bj][m][1] * rsc;
;                 if (ACT == 1) {
; #pragma unroll
;                     for (int j = 0; j < 4; ++j) { v0[j] = silu_(v0[j]); v1[j] = silu_(v1[j]); } }
;                 if (ACT == 2) {
; #pragma unroll
;                     for (int j = 0; j < 4; ++j) { v0[j] = sigm(v0[j]); v1[j] = sigm(v1[j]); } }
;                 u32x4 w; w[0] = pk2(v0[0], v0[1]); w[1] = pk2(v0[2], v0[3]); w[2] = pk2(v1[0], v1[1]); w[3] = pk2(v1[2], v1[3]);
;                 *(u32x4*)(rowp + bj * HALF) = w;
	global_store_dwordx4 v[130:131], v[170:173], off
	v_pk_mul_f32 v[182:183], v[70:71], v[180:181] op_sel_hi:[1,0]
	s_nop 0
	v_pk_mul_f32 v[172:173], v[68:69], v[180:181] op_sel_hi:[1,0]
	v_pk_mul_f32 v[170:171], v[66:67], v[180:181] op_sel_hi:[1,0]
	v_mul_f32_e32 v179, 0xbfb8aa3b, v172
	v_exp_f32_e32 v179, v179
	v_pk_mul_f32 v[180:181], v[64:65], v[180:181] op_sel_hi:[1,0]
	v_add_f32_e32 v179, 1.0, v179
	v_rcp_f32_e32 v184, v179
	v_mul_f32_e32 v179, 0xbfb8aa3b, v180
	v_exp_f32_e32 v179, v179
	s_nop 0
	v_add_f32_e32 v179, 1.0, v179
	v_rcp_f32_e32 v186, v179
	v_mul_f32_e32 v179, 0xbfb8aa3b, v173
	v_exp_f32_e32 v179, v179
	s_nop 0
	v_add_f32_e32 v179, 1.0, v179
	v_rcp_f32_e32 v185, v179
	v_mul_f32_e32 v179, 0xbfb8aa3b, v181
	v_exp_f32_e32 v179, v179
	v_pk_mul_f32 v[172:173], v[172:173], v[184:185]
	v_add_f32_e32 v179, 1.0, v179
	v_rcp_f32_e32 v187, v179
	v_mul_f32_e32 v179, 0xbfb8aa3b, v182
	v_exp_f32_e32 v179, v179
	v_pk_mul_f32 v[180:181], v[180:181], v[186:187]
	v_add_f32_e32 v179, 1.0, v179
	v_rcp_f32_e32 v184, v179
	v_mul_f32_e32 v179, 0xbfb8aa3b, v170
	v_exp_f32_e32 v179, v179
	s_nop 0
	v_add_f32_e32 v179, 1.0, v179
	v_rcp_f32_e32 v186, v179
	v_mul_f32_e32 v179, 0xbfb8aa3b, v183
	v_exp_f32_e32 v179, v179
	s_nop 0
	v_add_f32_e32 v179, 1.0, v179
	v_rcp_f32_e32 v185, v179
	v_mul_f32_e32 v179, 0xbfb8aa3b, v171
	v_exp_f32_e32 v179, v179
	v_pk_mul_f32 v[182:183], v[182:183], v[184:185]
	v_add_f32_e32 v179, 1.0, v179
	v_rcp_f32_e32 v187, v179
	s_nop 0
	v_pk_mul_f32 v[184:185], v[170:171], v[186:187]
	v_cvt_pk_bf16_f32 v170, v172, v173
	v_cvt_pk_bf16_f32 v171, v182, v183
	v_cvt_pk_bf16_f32 v172, v180, v181
	v_cvt_pk_bf16_f32 v173, v184, v185
	ds_bpermute_b32 v170, v193, v170
	ds_bpermute_b32 v171, v193, v171
	ds_bpermute_b32 v172, v193, v172
	ds_bpermute_b32 v173, v193, v173
	s_waitcnt lgkmcnt(0)
	global_store_dwordx4 v[130:131], v[170:173], off offset:256
	v_lshl_add_u64 v[130:131], v[128:129], 0, v[156:157]
	s_nop 1
	v_mov_b32_e32 v170, v240
	v_fmamk_f32 v170, v170, 0x3a800000, v175
	v_rsq_f32_e32 v180, v170
	s_nop 0
	v_pk_mul_f32 v[172:173], v[60:61], v[180:181] op_sel_hi:[1,0]
	s_nop 0
	v_mul_f32_e32 v179, 0xbfb8aa3b, v172
	v_exp_f32_e32 v179, v179
	v_pk_mul_f32 v[184:185], v[56:57], v[180:181] op_sel_hi:[1,0]
	v_pk_mul_f32 v[170:171], v[62:63], v[180:181] op_sel_hi:[1,0]
	v_pk_mul_f32 v[182:183], v[58:59], v[180:181] op_sel_hi:[1,0]
	v_add_f32_e32 v179, 1.0, v179
	v_rcp_f32_e32 v186, v179
	v_mul_f32_e32 v179, 0xbfb8aa3b, v184
	v_exp_f32_e32 v179, v179
	s_nop 0
	v_add_f32_e32 v179, 1.0, v179
	v_rcp_f32_e32 v188, v179
	v_mul_f32_e32 v179, 0xbfb8aa3b, v173
	v_exp_f32_e32 v179, v179
	s_nop 0
	v_add_f32_e32 v179, 1.0, v179
	v_rcp_f32_e32 v187, v179
	v_mul_f32_e32 v179, 0xbfb8aa3b, v185
	v_exp_f32_e32 v179, v179
	v_pk_mul_f32 v[172:173], v[172:173], v[186:187]
	v_add_f32_e32 v179, 1.0, v179
	v_rcp_f32_e32 v189, v179
	v_mul_f32_e32 v179, 0xbfb8aa3b, v170
	v_exp_f32_e32 v179, v179
	v_pk_mul_f32 v[184:185], v[184:185], v[188:189]
	v_add_f32_e32 v179, 1.0, v179
	v_rcp_f32_e32 v186, v179
	v_mul_f32_e32 v179, 0xbfb8aa3b, v182
	v_exp_f32_e32 v179, v179
	s_nop 0
	v_add_f32_e32 v179, 1.0, v179
	v_rcp_f32_e32 v188, v179
	v_mul_f32_e32 v179, 0xbfb8aa3b, v171
	v_exp_f32_e32 v179, v179
	s_nop 0
	v_add_f32_e32 v179, 1.0, v179
	v_rcp_f32_e32 v187, v179
	s_nop 0
	v_pk_mul_f32 v[186:187], v[170:171], v[186:187]
	v_mul_f32_e32 v170, 0xbfb8aa3b, v183
	v_exp_f32_e32 v170, v170
	v_cvt_pk_bf16_f32 v171, v186, v187
	v_add_f32_e32 v170, 1.0, v170
	v_rcp_f32_e32 v189, v170
	v_cvt_pk_bf16_f32 v170, v172, v173
	v_cvt_pk_bf16_f32 v172, v184, v185
	v_pk_mul_f32 v[182:183], v[182:183], v[188:189]
	s_nop 0
	v_cvt_pk_bf16_f32 v173, v182, v183
	ds_bpermute_b32 v170, v193, v170
	ds_bpermute_b32 v171, v193, v171
	ds_bpermute_b32 v172, v193, v172
	ds_bpermute_b32 v173, v193, v173
	s_waitcnt lgkmcnt(0)
	global_store_dwordx4 v[130:131], v[170:173], off
	v_pk_mul_f32 v[182:183], v[54:55], v[180:181] op_sel_hi:[1,0]
	s_nop 0
	v_pk_mul_f32 v[172:173], v[52:53], v[180:181] op_sel_hi:[1,0]
	v_pk_mul_f32 v[170:171], v[46:47], v[180:181] op_sel_hi:[1,0]
	v_mul_f32_e32 v179, 0xbfb8aa3b, v172
	v_exp_f32_e32 v179, v179
	v_pk_mul_f32 v[180:181], v[44:45], v[180:181] op_sel_hi:[1,0]
	v_add_f32_e32 v179, 1.0, v179
	v_rcp_f32_e32 v184, v179
	v_mul_f32_e32 v179, 0xbfb8aa3b, v180
	v_exp_f32_e32 v179, v179
	s_nop 0
	v_add_f32_e32 v179, 1.0, v179
	v_rcp_f32_e32 v186, v179
	v_mul_f32_e32 v179, 0xbfb8aa3b, v173
	v_exp_f32_e32 v179, v179
	s_nop 0
	v_add_f32_e32 v179, 1.0, v179
	v_rcp_f32_e32 v185, v179
	v_mul_f32_e32 v179, 0xbfb8aa3b, v181
	v_exp_f32_e32 v179, v179
	v_pk_mul_f32 v[172:173], v[172:173], v[184:185]
	v_add_f32_e32 v179, 1.0, v179
	v_rcp_f32_e32 v187, v179
	v_mul_f32_e32 v179, 0xbfb8aa3b, v182
	v_exp_f32_e32 v179, v179
	v_pk_mul_f32 v[180:181], v[180:181], v[186:187]
	v_add_f32_e32 v179, 1.0, v179
	v_rcp_f32_e32 v184, v179
	v_mul_f32_e32 v179, 0xbfb8aa3b, v170
	v_exp_f32_e32 v179, v179
	s_nop 0
	v_add_f32_e32 v179, 1.0, v179
	v_rcp_f32_e32 v186, v179
	v_mul_f32_e32 v179, 0xbfb8aa3b, v183
	v_exp_f32_e32 v179, v179
	s_nop 0
	v_add_f32_e32 v179, 1.0, v179
	v_rcp_f32_e32 v185, v179
	v_mul_f32_e32 v179, 0xbfb8aa3b, v171
	v_exp_f32_e32 v179, v179
	v_pk_mul_f32 v[182:183], v[182:183], v[184:185]
	v_add_f32_e32 v179, 1.0, v179
	v_rcp_f32_e32 v187, v179
	s_nop 0
	v_pk_mul_f32 v[184:185], v[170:171], v[186:187]
	v_cvt_pk_bf16_f32 v170, v172, v173
	v_cvt_pk_bf16_f32 v171, v182, v183
	v_cvt_pk_bf16_f32 v172, v180, v181
	v_cvt_pk_bf16_f32 v173, v184, v185
	ds_bpermute_b32 v170, v193, v170
	ds_bpermute_b32 v171, v193, v171
	ds_bpermute_b32 v172, v193, v172
	ds_bpermute_b32 v173, v193, v173
	s_waitcnt lgkmcnt(0)
; DI unsigned pk2(float a, float b) { f32x2 v = {a, b}; bf2_t r = __builtin_convertvector(v, bf2_t); return __builtin_bit_cast(unsigned, r); }
; DI float sigm(float x) { return __builtin_amdgcn_rcpf(1.f + __expf(-x)); }
; DI float silu_(float x) { return x * __builtin_amdgcn_rcpf(1.f + __expf(-x)); }
; template <int ACT>
; DI void epi_bf16(const f32x4 (&acc)[2][2][4][2], bf16_t* O, const int ldc, int wr, int wc, int fr, int fq, const float* ssrow = nullptr) {
;     ...
;         for (int m = 0; m < 4; ++m) {
;             bf16_t* rowp = O + (size_t)(ai * HALF + wr * 64 + m * 16 + fr) * ldc + wc * 32 + 8 * fq;
;             const float rsc = ssrow ? __builtin_amdgcn_rsqf(ssrow[ai * HALF + wr * 64 + m * 16 + fr] * (1.f / 1024.f) + EPS_) : 1.f;
; #pragma unroll
;             for (int bj = 0; bj < 2; ++bj) {
;                 f32x4 v0 = acc[ai][bj][m][0] * rsc, v1 = acc[ai][bj][m][1] * rsc;
;                 if (ACT == 1) {
; #pragma unroll
;                     for (int j = 0; j < 4; ++j) { v0[j] = silu_(v0[j]); v1[j] = silu_(v1[j]); } }
;                 if (ACT == 2) {
; #pragma unroll
;                     for (int j = 0; j < 4; ++j) { v0[j] = sigm(v0[j]); v1[j] = sigm(v1[j]); } }
;                 u32x4 w; w[0] = pk2(v0[0], v0[1]); w[1] = pk2(v0[2], v0[3]); w[2] = pk2(v1[0], v1[1]); w[3] = pk2(v1[2], v1[3]);
;                 *(u32x4*)(rowp + bj * HALF) = w;
	global_store_dwordx4 v[130:131], v[170:173], off offset:256
	v_lshl_add_u64 v[130:131], v[128:129], 0, v[158:159]
	s_nop 1
	v_mov_b32_e32 v170, v241
	v_fmamk_f32 v170, v170, 0x3a800000, v175
	v_rsq_f32_e32 v180, v170
	s_nop 0
	v_pk_mul_f32 v[172:173], v[48:49], v[180:181] op_sel_hi:[1,0]
	s_nop 0
	v_mul_f32_e32 v179, 0xbfb8aa3b, v172
	v_exp_f32_e32 v179, v179
	v_pk_mul_f32 v[184:185], v[40:41], v[180:181] op_sel_hi:[1,0]
	v_pk_mul_f32 v[170:171], v[50:51], v[180:181] op_sel_hi:[1,0]
	v_pk_mul_f32 v[182:183], v[42:43], v[180:181] op_sel_hi:[1,0]
	v_add_f32_e32 v179, 1.0, v179
	v_rcp_f32_e32 v186, v179
	v_mul_f32_e32 v179, 0xbfb8aa3b, v184
	v_exp_f32_e32 v179, v179
	s_nop 0
	v_add_f32_e32 v179, 1.0, v179
	v_rcp_f32_e32 v188, v179
	v_mul_f32_e32 v179, 0xbfb8aa3b, v173
	v_exp_f32_e32 v179, v179
	s_nop 0
	v_add_f32_e32 v179, 1.0, v179
	v_rcp_f32_e32 v187, v179
	v_mul_f32_e32 v179, 0xbfb8aa3b, v185
	v_exp_f32_e32 v179, v179
	v_pk_mul_f32 v[172:173], v[172:173], v[186:187]
	v_add_f32_e32 v179, 1.0, v179
	v_rcp_f32_e32 v189, v179
	v_mul_f32_e32 v179, 0xbfb8aa3b, v170
	v_exp_f32_e32 v179, v179
	v_pk_mul_f32 v[184:185], v[184:185], v[188:189]
	v_add_f32_e32 v179, 1.0, v179
	v_rcp_f32_e32 v186, v179
	v_mul_f32_e32 v179, 0xbfb8aa3b, v182
	v_exp_f32_e32 v179, v179
	s_nop 0
	v_add_f32_e32 v179, 1.0, v179
	v_rcp_f32_e32 v188, v179
	v_mul_f32_e32 v179, 0xbfb8aa3b, v171
	v_exp_f32_e32 v179, v179
	s_nop 0
	v_add_f32_e32 v179, 1.0, v179
	v_rcp_f32_e32 v187, v179
	s_nop 0
	v_pk_mul_f32 v[186:187], v[170:171], v[186:187]
	v_mul_f32_e32 v170, 0xbfb8aa3b, v183
	v_exp_f32_e32 v170, v170
	v_cvt_pk_bf16_f32 v171, v186, v187
	v_add_f32_e32 v170, 1.0, v170
	v_rcp_f32_e32 v189, v170
	v_cvt_pk_bf16_f32 v170, v172, v173
	v_cvt_pk_bf16_f32 v172, v184, v185
	v_pk_mul_f32 v[182:183], v[182:183], v[188:189]
	s_nop 0
	v_cvt_pk_bf16_f32 v173, v182, v183
	ds_bpermute_b32 v170, v193, v170
	ds_bpermute_b32 v171, v193, v171
	ds_bpermute_b32 v172, v193, v172
	ds_bpermute_b32 v173, v193, v173
	s_waitcnt lgkmcnt(0)
	global_store_dwordx4 v[130:131], v[170:173], off
	v_pk_mul_f32 v[182:183], v[38:39], v[180:181] op_sel_hi:[1,0]
	s_nop 0
	v_pk_mul_f32 v[172:173], v[36:37], v[180:181] op_sel_hi:[1,0]
	v_pk_mul_f32 v[170:171], v[30:31], v[180:181] op_sel_hi:[1,0]
	v_mul_f32_e32 v179, 0xbfb8aa3b, v172
	v_exp_f32_e32 v179, v179
	v_pk_mul_f32 v[180:181], v[28:29], v[180:181] op_sel_hi:[1,0]
	v_add_f32_e32 v179, 1.0, v179
	v_rcp_f32_e32 v184, v179
	v_mul_f32_e32 v179, 0xbfb8aa3b, v180
	v_exp_f32_e32 v179, v179
	s_nop 0
	v_add_f32_e32 v179, 1.0, v179
	v_rcp_f32_e32 v186, v179
	v_mul_f32_e32 v179, 0xbfb8aa3b, v173
	v_exp_f32_e32 v179, v179
	s_nop 0
	v_add_f32_e32 v179, 1.0, v179
	v_rcp_f32_e32 v185, v179
	v_mul_f32_e32 v179, 0xbfb8aa3b, v181
	v_exp_f32_e32 v179, v179
	v_pk_mul_f32 v[172:173], v[172:173], v[184:185]
	v_add_f32_e32 v179, 1.0, v179
	v_rcp_f32_e32 v187, v179
	v_mul_f32_e32 v179, 0xbfb8aa3b, v182
	v_exp_f32_e32 v179, v179
	v_pk_mul_f32 v[180:181], v[180:181], v[186:187]
	v_add_f32_e32 v179, 1.0, v179
	v_rcp_f32_e32 v184, v179
	v_mul_f32_e32 v179, 0xbfb8aa3b, v170
	v_exp_f32_e32 v179, v179
	s_nop 0
	v_add_f32_e32 v179, 1.0, v179
	v_rcp_f32_e32 v186, v179
	v_mul_f32_e32 v179, 0xbfb8aa3b, v183
	v_exp_f32_e32 v179, v179
	s_nop 0
	v_add_f32_e32 v179, 1.0, v179
	v_rcp_f32_e32 v185, v179
	v_mul_f32_e32 v179, 0xbfb8aa3b, v171
	v_exp_f32_e32 v179, v179
	v_pk_mul_f32 v[182:183], v[182:183], v[184:185]
	v_add_f32_e32 v179, 1.0, v179
	v_rcp_f32_e32 v187, v179
	s_nop 0
	v_pk_mul_f32 v[184:185], v[170:171], v[186:187]
	v_cvt_pk_bf16_f32 v170, v172, v173
	v_cvt_pk_bf16_f32 v171, v182, v183
	v_cvt_pk_bf16_f32 v172, v180, v181
	v_cvt_pk_bf16_f32 v173, v184, v185
	ds_bpermute_b32 v170, v193, v170
	ds_bpermute_b32 v171, v193, v171
	ds_bpermute_b32 v172, v193, v172
	ds_bpermute_b32 v173, v193, v173
	s_waitcnt lgkmcnt(0)
	global_store_dwordx4 v[130:131], v[170:173], off offset:256
	v_lshl_add_u64 v[130:131], v[128:129], 0, v[160:161]
	s_nop 1
	v_mov_b32_e32 v170, v242
	v_fmamk_f32 v170, v170, 0x3a800000, v175
	v_rsq_f32_e32 v180, v170
	s_nop 0
	v_pk_mul_f32 v[172:173], v[32:33], v[180:181] op_sel_hi:[1,0]
	s_nop 0
	v_mul_f32_e32 v179, 0xbfb8aa3b, v172
	v_exp_f32_e32 v179, v179
	v_pk_mul_f32 v[184:185], v[24:25], v[180:181] op_sel_hi:[1,0]
	v_pk_mul_f32 v[170:171], v[34:35], v[180:181] op_sel_hi:[1,0]
	v_pk_mul_f32 v[182:183], v[26:27], v[180:181] op_sel_hi:[1,0]
	v_add_f32_e32 v179, 1.0, v179
	v_rcp_f32_e32 v186, v179
	v_mul_f32_e32 v179, 0xbfb8aa3b, v184
	v_exp_f32_e32 v179, v179
	s_nop 0
	v_add_f32_e32 v179, 1.0, v179
	v_rcp_f32_e32 v188, v179
	v_mul_f32_e32 v179, 0xbfb8aa3b, v173
	v_exp_f32_e32 v179, v179
	s_nop 0
	v_add_f32_e32 v179, 1.0, v179
	v_rcp_f32_e32 v187, v179
	v_mul_f32_e32 v179, 0xbfb8aa3b, v185
	v_exp_f32_e32 v179, v179
	v_pk_mul_f32 v[172:173], v[172:173], v[186:187]
	v_add_f32_e32 v179, 1.0, v179
	v_rcp_f32_e32 v189, v179
	v_mul_f32_e32 v179, 0xbfb8aa3b, v170
	v_exp_f32_e32 v179, v179
	v_pk_mul_f32 v[184:185], v[184:185], v[188:189]
	v_add_f32_e32 v179, 1.0, v179
	v_rcp_f32_e32 v186, v179
	v_mul_f32_e32 v179, 0xbfb8aa3b, v182
	v_exp_f32_e32 v179, v179
	s_nop 0
	v_add_f32_e32 v179, 1.0, v179
	v_rcp_f32_e32 v188, v179
	v_mul_f32_e32 v179, 0xbfb8aa3b, v171
	v_exp_f32_e32 v179, v179
	s_nop 0
	v_add_f32_e32 v179, 1.0, v179
	v_rcp_f32_e32 v187, v179
	s_nop 0
	v_pk_mul_f32 v[186:187], v[170:171], v[186:187]
	v_mul_f32_e32 v170, 0xbfb8aa3b, v183
	v_exp_f32_e32 v170, v170
	v_cvt_pk_bf16_f32 v171, v186, v187
	v_add_f32_e32 v170, 1.0, v170
	v_rcp_f32_e32 v189, v170
	v_cvt_pk_bf16_f32 v170, v172, v173
	v_cvt_pk_bf16_f32 v172, v184, v185
	v_pk_mul_f32 v[182:183], v[182:183], v[188:189]
	s_nop 0
	v_cvt_pk_bf16_f32 v173, v182, v183
	ds_bpermute_b32 v170, v193, v170
	ds_bpermute_b32 v171, v193, v171
	ds_bpermute_b32 v172, v193, v172
	ds_bpermute_b32 v173, v193, v173
	s_waitcnt lgkmcnt(0)
; DI unsigned pk2(float a, float b) { f32x2 v = {a, b}; bf2_t r = __builtin_convertvector(v, bf2_t); return __builtin_bit_cast(unsigned, r); }
; DI float sigm(float x) { return __builtin_amdgcn_rcpf(1.f + __expf(-x)); }
; DI float silu_(float x) { return x * __builtin_amdgcn_rcpf(1.f + __expf(-x)); }
; template <int ACT>
; DI void epi_bf16(const f32x4 (&acc)[2][2][4][2], bf16_t* O, const int ldc, int wr, int wc, int fr, int fq, const float* ssrow = nullptr) {
;     ...
;         for (int m = 0; m < 4; ++m) {
;             bf16_t* rowp = O + (size_t)(ai * HALF + wr * 64 + m * 16 + fr) * ldc + wc * 32 + 8 * fq;
;             const float rsc = ssrow ? __builtin_amdgcn_rsqf(ssrow[ai * HALF + wr * 64 + m * 16 + fr] * (1.f / 1024.f) + EPS_) : 1.f;
; #pragma unroll
;             for (int bj = 0; bj < 2; ++bj) {
;                 f32x4 v0 = acc[ai][bj][m][0] * rsc, v1 = acc[ai][bj][m][1] * rsc;
;                 if (ACT == 1) {
; #pragma unroll
;                     for (int j = 0; j < 4; ++j) { v0[j] = silu_(v0[j]); v1[j] = silu_(v1[j]); } }
;                 if (ACT == 2) {
; #pragma unroll
;                     for (int j = 0; j < 4; ++j) { v0[j] = sigm(v0[j]); v1[j] = sigm(v1[j]); } }
;                 u32x4 w; w[0] = pk2(v0[0], v0[1]); w[1] = pk2(v0[2], v0[3]); w[2] = pk2(v1[0], v1[1]); w[3] = pk2(v1[2], v1[3]);
;                 *(u32x4*)(rowp + bj * HALF) = w;
	global_store_dwordx4 v[130:131], v[170:173], off
	v_pk_mul_f32 v[182:183], v[22:23], v[180:181] op_sel_hi:[1,0]
	s_nop 0
	v_pk_mul_f32 v[172:173], v[20:21], v[180:181] op_sel_hi:[1,0]
	v_pk_mul_f32 v[170:171], v[14:15], v[180:181] op_sel_hi:[1,0]
	v_mul_f32_e32 v179, 0xbfb8aa3b, v172
	v_exp_f32_e32 v179, v179
	v_pk_mul_f32 v[180:181], v[12:13], v[180:181] op_sel_hi:[1,0]
	v_add_f32_e32 v179, 1.0, v179
	v_rcp_f32_e32 v184, v179
	v_mul_f32_e32 v179, 0xbfb8aa3b, v180
	v_exp_f32_e32 v179, v179
	s_nop 0
	v_add_f32_e32 v179, 1.0, v179
	v_rcp_f32_e32 v186, v179
	v_mul_f32_e32 v179, 0xbfb8aa3b, v173
	v_exp_f32_e32 v179, v179
	s_nop 0
	v_add_f32_e32 v179, 1.0, v179
	v_rcp_f32_e32 v185, v179
	v_mul_f32_e32 v179, 0xbfb8aa3b, v181
	v_exp_f32_e32 v179, v179
	v_pk_mul_f32 v[172:173], v[172:173], v[184:185]
	v_add_f32_e32 v179, 1.0, v179
	v_rcp_f32_e32 v187, v179
	v_mul_f32_e32 v179, 0xbfb8aa3b, v182
	v_exp_f32_e32 v179, v179
	v_pk_mul_f32 v[180:181], v[180:181], v[186:187]
	v_add_f32_e32 v179, 1.0, v179
	v_rcp_f32_e32 v184, v179
	v_mul_f32_e32 v179, 0xbfb8aa3b, v170
	v_exp_f32_e32 v179, v179
	s_nop 0
	v_add_f32_e32 v179, 1.0, v179
	v_rcp_f32_e32 v186, v179
	v_mul_f32_e32 v179, 0xbfb8aa3b, v183
	v_exp_f32_e32 v179, v179
	s_nop 0
	v_add_f32_e32 v179, 1.0, v179
	v_rcp_f32_e32 v185, v179
	v_mul_f32_e32 v179, 0xbfb8aa3b, v171
	v_exp_f32_e32 v179, v179
	v_pk_mul_f32 v[182:183], v[182:183], v[184:185]
	v_add_f32_e32 v179, 1.0, v179
	v_rcp_f32_e32 v187, v179
	s_nop 0
	v_pk_mul_f32 v[184:185], v[170:171], v[186:187]
	v_cvt_pk_bf16_f32 v170, v172, v173
	v_cvt_pk_bf16_f32 v171, v182, v183
	v_cvt_pk_bf16_f32 v172, v180, v181
	v_cvt_pk_bf16_f32 v173, v184, v185
	ds_bpermute_b32 v170, v193, v170
	ds_bpermute_b32 v171, v193, v171
	ds_bpermute_b32 v172, v193, v172
	ds_bpermute_b32 v173, v193, v173
	s_waitcnt lgkmcnt(0)
	global_store_dwordx4 v[130:131], v[170:173], off offset:256
	s_nop 1
	v_mov_b32_e32 v130, v243
	v_fmamk_f32 v130, v130, 0x3a800000, v175
	v_rsq_f32_e32 v170, v130
	v_lshl_add_u64 v[172:173], v[128:129], 0, v[162:163]
	v_pk_mul_f32 v[130:131], v[16:17], v[170:171] op_sel_hi:[1,0]
	v_pk_mul_f32 v[128:129], v[18:19], v[170:171] op_sel_hi:[1,0]
	v_pk_mul_f32 v[180:181], v[10:11], v[170:171] op_sel_hi:[1,0]
	v_pk_mul_f32 v[182:183], v[8:9], v[170:171] op_sel_hi:[1,0]
	v_mul_f32_e32 v171, 0xbfb8aa3b, v130
	v_exp_f32_e32 v171, v171
	s_nop 0
	v_add_f32_e32 v171, 1.0, v171
	v_rcp_f32_e32 v184, v171
	v_mul_f32_e32 v171, 0xbfb8aa3b, v182
	v_exp_f32_e32 v171, v171
	s_nop 0
	v_add_f32_e32 v171, 1.0, v171
	v_rcp_f32_e32 v186, v171
	v_mul_f32_e32 v171, 0xbfb8aa3b, v131
	v_exp_f32_e32 v171, v171
	s_nop 0
	v_add_f32_e32 v171, 1.0, v171
	v_rcp_f32_e32 v185, v171
	v_mul_f32_e32 v171, 0xbfb8aa3b, v183
	v_exp_f32_e32 v171, v171
	v_pk_mul_f32 v[130:131], v[130:131], v[184:185]
	v_add_f32_e32 v171, 1.0, v171
	v_rcp_f32_e32 v187, v171
	v_mul_f32_e32 v171, 0xbfb8aa3b, v128
	v_exp_f32_e32 v171, v171
	v_pk_mul_f32 v[182:183], v[182:183], v[186:187]
	v_add_f32_e32 v171, 1.0, v171
	v_rcp_f32_e32 v184, v171
	v_mul_f32_e32 v171, 0xbfb8aa3b, v180
	v_exp_f32_e32 v171, v171
	s_nop 0
	v_add_f32_e32 v171, 1.0, v171
	v_rcp_f32_e32 v186, v171
	v_mul_f32_e32 v171, 0xbfb8aa3b, v129
	v_exp_f32_e32 v171, v171
	s_nop 0
	v_add_f32_e32 v171, 1.0, v171
	v_rcp_f32_e32 v185, v171
	s_nop 0
	v_pk_mul_f32 v[184:185], v[128:129], v[184:185]
	v_mul_f32_e32 v128, 0xbfb8aa3b, v181
	v_exp_f32_e32 v128, v128
	v_cvt_pk_bf16_f32 v129, v184, v185
	v_add_f32_e32 v128, 1.0, v128
	v_rcp_f32_e32 v187, v128
	v_cvt_pk_bf16_f32 v128, v130, v131
	v_cvt_pk_bf16_f32 v130, v182, v183
	v_pk_mul_f32 v[180:181], v[180:181], v[186:187]
	s_nop 0
	v_cvt_pk_bf16_f32 v131, v180, v181
	ds_bpermute_b32 v128, v193, v128
	ds_bpermute_b32 v129, v193, v129
	ds_bpermute_b32 v130, v193, v130
	ds_bpermute_b32 v131, v193, v131
	s_waitcnt lgkmcnt(0)
	global_store_dwordx4 v[172:173], v[128:131], off
	v_pk_mul_f32 v[172:173], v[6:7], v[170:171] op_sel_hi:[1,0]
	s_nop 0
	v_pk_mul_f32 v[130:131], v[4:5], v[170:171] op_sel_hi:[1,0]
	v_pk_mul_f32 v[128:129], v[2:3], v[170:171] op_sel_hi:[1,0]
	v_mul_f32_e32 v179, 0xbfb8aa3b, v130
	v_exp_f32_e32 v179, v179
	v_pk_mul_f32 v[170:171], v[0:1], v[170:171] op_sel_hi:[1,0]
	v_add_f32_e32 v179, 1.0, v179
	v_rcp_f32_e32 v180, v179
	v_mul_f32_e32 v179, 0xbfb8aa3b, v170
	v_exp_f32_e32 v179, v179
	s_nop 0
	v_add_f32_e32 v179, 1.0, v179
	v_rcp_f32_e32 v182, v179
	v_mul_f32_e32 v179, 0xbfb8aa3b, v131
	v_exp_f32_e32 v179, v179
	s_nop 0
	v_add_f32_e32 v179, 1.0, v179
	v_rcp_f32_e32 v181, v179
	v_mul_f32_e32 v179, 0xbfb8aa3b, v171
	v_exp_f32_e32 v179, v179
	v_pk_mul_f32 v[130:131], v[130:131], v[180:181]
	v_add_f32_e32 v179, 1.0, v179
	v_rcp_f32_e32 v183, v179
	s_nop 0
	v_pk_mul_f32 v[180:181], v[170:171], v[182:183]
	v_mul_f32_e32 v171, 0xbfb8aa3b, v128
	v_exp_f32_e32 v171, v171
	v_mul_f32_e32 v170, 0xbfb8aa3b, v172
	v_exp_f32_e32 v170, v170
	v_add_f32_e32 v171, 1.0, v171
	v_rcp_f32_e32 v182, v171
	v_mul_f32_e32 v171, 0xbfb8aa3b, v173
	v_exp_f32_e32 v171, v171
	v_add_f32_e32 v170, 1.0, v170
	v_rcp_f32_e32 v170, v170
	v_add_f32_e32 v171, 1.0, v171
	v_rcp_f32_e32 v171, v171
	s_nop 0
	v_pk_mul_f32 v[172:173], v[172:173], v[170:171]
	v_mul_f32_e32 v170, 0xbfb8aa3b, v129
	v_exp_f32_e32 v170, v170
	s_nop 0
	v_add_f32_e32 v170, 1.0, v170
	v_rcp_f32_e32 v183, v170
	s_nop 0
	v_pk_mul_f32 v[170:171], v[128:129], v[182:183]
	v_cvt_pk_bf16_f32 v128, v130, v131
	v_cvt_pk_bf16_f32 v129, v172, v173
	v_cvt_pk_bf16_f32 v130, v180, v181
; DI unsigned pk2(float a, float b) { f32x2 v = {a, b}; bf2_t r = __builtin_convertvector(v, bf2_t); return __builtin_bit_cast(unsigned, r); }
; DI float sigm(float x) { return __builtin_amdgcn_rcpf(1.f + __expf(-x)); }
; DI float silu_(float x) { return x * __builtin_amdgcn_rcpf(1.f + __expf(-x)); }
; template <int ACT>
; DI void epi_bf16(const f32x4 (&acc)[2][2][4][2], bf16_t* O, const int ldc, int wr, int wc, int fr, int fq, const float* ssrow = nullptr) {
;     ...
;         for (int m = 0; m < 4; ++m) {
;             bf16_t* rowp = O + (size_t)(ai * HALF + wr * 64 + m * 16 + fr) * ldc + wc * 32 + 8 * fq;
;             const float rsc = ssrow ? __builtin_amdgcn_rsqf(ssrow[ai * HALF + wr * 64 + m * 16 + fr] * (1.f / 1024.f) + EPS_) : 1.f;
; #pragma unroll
;             for (int bj = 0; bj < 2; ++bj) {
;                 f32x4 v0 = acc[ai][bj][m][0] * rsc, v1 = acc[ai][bj][m][1] * rsc;
;                 if (ACT == 1) {
; #pragma unroll
;                     for (int j = 0; j < 4; ++j) { v0[j] = silu_(v0[j]); v1[j] = silu_(v1[j]); } }
;                 if (ACT == 2) {
; #pragma unroll
;                     for (int j = 0; j < 4; ++j) { v0[j] = sigm(v0[j]); v1[j] = sigm(v1[j]); } }
;                 u32x4 w; w[0] = pk2(v0[0], v0[1]); w[1] = pk2(v0[2], v0[3]); w[2] = pk2(v1[0], v1[1]); w[3] = pk2(v1[2], v1[3]);
;                 *(u32x4*)(rowp + bj * HALF) = w;
;             }
.LBB0_755:
	s_andn2_b64 vcc, exec, s[2:3]
	s_cbranch_vccnz .LBB0_748
	global_load_dword v236, v[168:169], off
	global_load_dword v237, v[168:169], off offset:64
	global_load_dword v238, v[168:169], off offset:128
	global_load_dword v239, v[168:169], off offset:192
	global_load_dword v240, v[168:169], off offset:512
	global_load_dword v241, v[168:169], off offset:576
	global_load_dword v242, v[168:169], off offset:640
	global_load_dword v243, v[168:169], off offset:704
	v_readlane_b32 s2, v246, 51
	v_readlane_b32 s3, v246, 52
	s_add_u32 s4, s2, s27
	s_addc_u32 s15, s3, s15
	s_ashr_i32 s31, s30, 31
	s_lshl_b64 s[2:3], s[30:31], 1
	s_add_u32 s28, s4, s2
	s_addc_u32 s29, s15, s3
	s_lshl_b32 s2, s74, 1
	s_add_u32 s2, s28, s2
	s_addc_u32 s3, s29, 0
	s_waitcnt vmcnt(0)
	v_mov_b32_e32 v128, v236
	v_fmamk_f32 v128, v128, 0x3a800000, v175
	v_rsq_f32_e32 v130, v128
	v_lshl_add_u64 v[128:129], s[2:3], 0, v[132:133]
	v_lshl_add_u64 v[170:171], v[128:129], 0, v[148:149]
	v_pk_mul_f32 v[126:127], v[126:127], v[130:131] op_sel_hi:[1,0]
	v_pk_mul_f32 v[124:125], v[124:125], v[130:131] op_sel_hi:[1,0]
	v_pk_mul_f32 v[122:123], v[122:123], v[130:131] op_sel_hi:[1,0]
	v_pk_mul_f32 v[120:121], v[120:121], v[130:131] op_sel_hi:[1,0]
	v_pk_mul_f32 v[118:119], v[118:119], v[130:131] op_sel_hi:[1,0]
	v_pk_mul_f32 v[116:117], v[116:117], v[130:131] op_sel_hi:[1,0]
	v_pk_mul_f32 v[172:173], v[110:111], v[130:131] op_sel_hi:[1,0]
	v_pk_mul_f32 v[130:131], v[108:109], v[130:131] op_sel_hi:[1,0]
	v_cvt_pk_bf16_f32 v108, v124, v125
	v_cvt_pk_bf16_f32 v109, v126, v127
	v_cvt_pk_bf16_f32 v110, v120, v121
	v_cvt_pk_bf16_f32 v111, v122, v123
	ds_bpermute_b32 v108, v193, v108
	ds_bpermute_b32 v109, v193, v109
	ds_bpermute_b32 v110, v193, v110
	ds_bpermute_b32 v111, v193, v111
	v_cvt_pk_bf16_f32 v116, v116, v117
	v_cvt_pk_bf16_f32 v117, v118, v119
	v_cvt_pk_bf16_f32 v118, v130, v131
	v_cvt_pk_bf16_f32 v119, v172, v173
	ds_bpermute_b32 v116, v193, v116
	ds_bpermute_b32 v117, v193, v117
	ds_bpermute_b32 v118, v193, v118
	ds_bpermute_b32 v119, v193, v119
	s_waitcnt lgkmcnt(4)
	global_store_dwordx4 v[170:171], v[108:111], off
	s_waitcnt lgkmcnt(0)
	global_store_dwordx4 v[170:171], v[116:119], off offset:256
	v_lshl_add_u64 v[110:111], v[128:129], 0, v[150:151]
	s_nop 1
	v_mov_b32_e32 v108, v237
	v_fmamk_f32 v108, v108, 0x3a800000, v175
	v_rsq_f32_e32 v108, v108
	s_nop 0
	v_pk_mul_f32 v[114:115], v[114:115], v[108:109] op_sel_hi:[1,0]
	v_pk_mul_f32 v[112:113], v[112:113], v[108:109] op_sel_hi:[1,0]
	v_pk_mul_f32 v[106:107], v[106:107], v[108:109] op_sel_hi:[1,0]
	v_pk_mul_f32 v[104:105], v[104:105], v[108:109] op_sel_hi:[1,0]
	v_pk_mul_f32 v[102:103], v[102:103], v[108:109] op_sel_hi:[1,0]
	v_pk_mul_f32 v[100:101], v[100:101], v[108:109] op_sel_hi:[1,0]
	v_pk_mul_f32 v[116:117], v[94:95], v[108:109] op_sel_hi:[1,0]
	v_pk_mul_f32 v[108:109], v[92:93], v[108:109] op_sel_hi:[1,0]
	v_cvt_pk_bf16_f32 v92, v112, v113
	v_cvt_pk_bf16_f32 v93, v114, v115
	v_cvt_pk_bf16_f32 v94, v104, v105
	v_cvt_pk_bf16_f32 v95, v106, v107
	ds_bpermute_b32 v92, v193, v92
	ds_bpermute_b32 v93, v193, v93
	ds_bpermute_b32 v94, v193, v94
	ds_bpermute_b32 v95, v193, v95
	v_cvt_pk_bf16_f32 v100, v100, v101
	v_cvt_pk_bf16_f32 v101, v102, v103
	v_cvt_pk_bf16_f32 v102, v108, v109
	v_cvt_pk_bf16_f32 v103, v116, v117
	ds_bpermute_b32 v100, v193, v100
	ds_bpermute_b32 v101, v193, v101
	ds_bpermute_b32 v102, v193, v102
	ds_bpermute_b32 v103, v193, v103
	s_waitcnt lgkmcnt(4)
	global_store_dwordx4 v[110:111], v[92:95], off
	s_waitcnt lgkmcnt(0)
	global_store_dwordx4 v[110:111], v[100:103], off offset:256
	v_lshl_add_u64 v[94:95], v[128:129], 0, v[152:153]
	s_nop 1
	v_mov_b32_e32 v92, v238
	v_fmamk_f32 v92, v92, 0x3a800000, v175
	v_rsq_f32_e32 v92, v92
	s_nop 0
	v_pk_mul_f32 v[98:99], v[98:99], v[92:93] op_sel_hi:[1,0]
	v_pk_mul_f32 v[96:97], v[96:97], v[92:93] op_sel_hi:[1,0]
	v_pk_mul_f32 v[90:91], v[90:91], v[92:93] op_sel_hi:[1,0]
	v_pk_mul_f32 v[88:89], v[88:89], v[92:93] op_sel_hi:[1,0]
	v_pk_mul_f32 v[86:87], v[86:87], v[92:93] op_sel_hi:[1,0]
	v_pk_mul_f32 v[84:85], v[84:85], v[92:93] op_sel_hi:[1,0]
	v_pk_mul_f32 v[100:101], v[78:79], v[92:93] op_sel_hi:[1,0]
	v_pk_mul_f32 v[92:93], v[76:77], v[92:93] op_sel_hi:[1,0]
	v_cvt_pk_bf16_f32 v76, v96, v97
	v_cvt_pk_bf16_f32 v77, v98, v99
	v_cvt_pk_bf16_f32 v78, v88, v89
	v_cvt_pk_bf16_f32 v79, v90, v91
	ds_bpermute_b32 v76, v193, v76
	ds_bpermute_b32 v77, v193, v77
	ds_bpermute_b32 v78, v193, v78
	ds_bpermute_b32 v79, v193, v79
	v_cvt_pk_bf16_f32 v84, v84, v85
	v_cvt_pk_bf16_f32 v85, v86, v87
	v_cvt_pk_bf16_f32 v86, v92, v93
	v_cvt_pk_bf16_f32 v87, v100, v101
	ds_bpermute_b32 v84, v193, v84
	ds_bpermute_b32 v85, v193, v85
	ds_bpermute_b32 v86, v193, v86
	ds_bpermute_b32 v87, v193, v87
	s_waitcnt lgkmcnt(4)
	global_store_dwordx4 v[94:95], v[76:79], off
	s_waitcnt lgkmcnt(0)
	global_store_dwordx4 v[94:95], v[84:87], off offset:256
	v_lshl_add_u64 v[78:79], v[128:129], 0, v[154:155]
	s_nop 1
	v_mov_b32_e32 v76, v239
	v_fmamk_f32 v76, v76, 0x3a800000, v175
	v_rsq_f32_e32 v76, v76
	s_nop 0
	v_pk_mul_f32 v[82:83], v[82:83], v[76:77] op_sel_hi:[1,0]
	v_pk_mul_f32 v[80:81], v[80:81], v[76:77] op_sel_hi:[1,0]
	v_pk_mul_f32 v[74:75], v[74:75], v[76:77] op_sel_hi:[1,0]
	v_pk_mul_f32 v[72:73], v[72:73], v[76:77] op_sel_hi:[1,0]
	v_pk_mul_f32 v[70:71], v[70:71], v[76:77] op_sel_hi:[1,0]
	v_pk_mul_f32 v[68:69], v[68:69], v[76:77] op_sel_hi:[1,0]
	v_pk_mul_f32 v[84:85], v[66:67], v[76:77] op_sel_hi:[1,0]
	v_pk_mul_f32 v[76:77], v[64:65], v[76:77] op_sel_hi:[1,0]
	v_cvt_pk_bf16_f32 v64, v80, v81
	v_cvt_pk_bf16_f32 v65, v82, v83
	v_cvt_pk_bf16_f32 v66, v72, v73
	v_cvt_pk_bf16_f32 v67, v74, v75
	ds_bpermute_b32 v64, v193, v64
	ds_bpermute_b32 v65, v193, v65
	ds_bpermute_b32 v66, v193, v66
	ds_bpermute_b32 v67, v193, v67
	v_cvt_pk_bf16_f32 v68, v68, v69
	v_cvt_pk_bf16_f32 v69, v70, v71
	v_cvt_pk_bf16_f32 v70, v76, v77
	v_cvt_pk_bf16_f32 v71, v84, v85
	ds_bpermute_b32 v68, v193, v68
	ds_bpermute_b32 v69, v193, v69
	ds_bpermute_b32 v70, v193, v70
	ds_bpermute_b32 v71, v193, v71
	s_waitcnt lgkmcnt(4)
; DI unsigned pk2(float a, float b) { f32x2 v = {a, b}; bf2_t r = __builtin_convertvector(v, bf2_t); return __builtin_bit_cast(unsigned, r); }
; DI float sigm(float x) { return __builtin_amdgcn_rcpf(1.f + __expf(-x)); }
; DI float silu_(float x) { return x * __builtin_amdgcn_rcpf(1.f + __expf(-x)); }
; template <int ACT>
; DI void epi_bf16(const f32x4 (&acc)[2][2][4][2], bf16_t* O, const int ldc, int wr, int wc, int fr, int fq, const float* ssrow = nullptr) {
;     ...
;         for (int m = 0; m < 4; ++m) {
;             bf16_t* rowp = O + (size_t)(ai * HALF + wr * 64 + m * 16 + fr) * ldc + wc * 32 + 8 * fq;
;             const float rsc = ssrow ? __builtin_amdgcn_rsqf(ssrow[ai * HALF + wr * 64 + m * 16 + fr] * (1.f / 1024.f) + EPS_) : 1.f;
; #pragma unroll
;             for (int bj = 0; bj < 2; ++bj) {
;                 f32x4 v0 = acc[ai][bj][m][0] * rsc, v1 = acc[ai][bj][m][1] * rsc;
;                 if (ACT == 1) {
; #pragma unroll
;                     for (int j = 0; j < 4; ++j) { v0[j] = silu_(v0[j]); v1[j] = silu_(v1[j]); } }
;                 if (ACT == 2) {
; #pragma unroll
;                     for (int j = 0; j < 4; ++j) { v0[j] = sigm(v0[j]); v1[j] = sigm(v1[j]); } }
;                 u32x4 w; w[0] = pk2(v0[0], v0[1]); w[1] = pk2(v0[2], v0[3]); w[2] = pk2(v1[0], v1[1]); w[3] = pk2(v1[2], v1[3]);
;                 *(u32x4*)(rowp + bj * HALF) = w;
;             }
	global_store_dwordx4 v[78:79], v[64:67], off
	s_waitcnt lgkmcnt(0)
	global_store_dwordx4 v[78:79], v[68:71], off offset:256
	v_lshl_add_u64 v[66:67], v[128:129], 0, v[156:157]
	s_nop 1
	v_mov_b32_e32 v64, v240
	v_fmamk_f32 v64, v64, 0x3a800000, v175
	v_rsq_f32_e32 v64, v64
	s_nop 0
	v_pk_mul_f32 v[62:63], v[62:63], v[64:65] op_sel_hi:[1,0]
	v_pk_mul_f32 v[60:61], v[60:61], v[64:65] op_sel_hi:[1,0]
	v_pk_mul_f32 v[58:59], v[58:59], v[64:65] op_sel_hi:[1,0]
	v_pk_mul_f32 v[56:57], v[56:57], v[64:65] op_sel_hi:[1,0]
	v_pk_mul_f32 v[54:55], v[54:55], v[64:65] op_sel_hi:[1,0]
	v_pk_mul_f32 v[52:53], v[52:53], v[64:65] op_sel_hi:[1,0]
	v_pk_mul_f32 v[68:69], v[46:47], v[64:65] op_sel_hi:[1,0]
	v_pk_mul_f32 v[64:65], v[44:45], v[64:65] op_sel_hi:[1,0]
	v_cvt_pk_bf16_f32 v44, v60, v61
	v_cvt_pk_bf16_f32 v45, v62, v63
	v_cvt_pk_bf16_f32 v46, v56, v57
	v_cvt_pk_bf16_f32 v47, v58, v59
	ds_bpermute_b32 v44, v193, v44
	ds_bpermute_b32 v45, v193, v45
	ds_bpermute_b32 v46, v193, v46
	ds_bpermute_b32 v47, v193, v47
	v_cvt_pk_bf16_f32 v52, v52, v53
	v_cvt_pk_bf16_f32 v53, v54, v55
	v_cvt_pk_bf16_f32 v54, v64, v65
	v_cvt_pk_bf16_f32 v55, v68, v69
	ds_bpermute_b32 v52, v193, v52
	ds_bpermute_b32 v53, v193, v53
	ds_bpermute_b32 v54, v193, v54
	ds_bpermute_b32 v55, v193, v55
	s_waitcnt lgkmcnt(4)
	global_store_dwordx4 v[66:67], v[44:47], off
	s_waitcnt lgkmcnt(0)
	global_store_dwordx4 v[66:67], v[52:55], off offset:256
	v_lshl_add_u64 v[46:47], v[128:129], 0, v[158:159]
	s_nop 1
	v_mov_b32_e32 v44, v241
	v_fmamk_f32 v44, v44, 0x3a800000, v175
	v_rsq_f32_e32 v44, v44
	s_nop 0
	v_pk_mul_f32 v[50:51], v[50:51], v[44:45] op_sel_hi:[1,0]
	v_pk_mul_f32 v[48:49], v[48:49], v[44:45] op_sel_hi:[1,0]
	v_pk_mul_f32 v[42:43], v[42:43], v[44:45] op_sel_hi:[1,0]
	v_pk_mul_f32 v[40:41], v[40:41], v[44:45] op_sel_hi:[1,0]
	v_pk_mul_f32 v[38:39], v[38:39], v[44:45] op_sel_hi:[1,0]
	v_pk_mul_f32 v[36:37], v[36:37], v[44:45] op_sel_hi:[1,0]
	v_pk_mul_f32 v[52:53], v[30:31], v[44:45] op_sel_hi:[1,0]
	v_pk_mul_f32 v[44:45], v[28:29], v[44:45] op_sel_hi:[1,0]
	v_cvt_pk_bf16_f32 v28, v48, v49
	v_cvt_pk_bf16_f32 v29, v50, v51
	v_cvt_pk_bf16_f32 v30, v40, v41
	v_cvt_pk_bf16_f32 v31, v42, v43
	ds_bpermute_b32 v28, v193, v28
	ds_bpermute_b32 v29, v193, v29
	ds_bpermute_b32 v30, v193, v30
	ds_bpermute_b32 v31, v193, v31
	v_cvt_pk_bf16_f32 v36, v36, v37
	v_cvt_pk_bf16_f32 v37, v38, v39
	v_cvt_pk_bf16_f32 v38, v44, v45
	v_cvt_pk_bf16_f32 v39, v52, v53
	ds_bpermute_b32 v36, v193, v36
	ds_bpermute_b32 v37, v193, v37
	ds_bpermute_b32 v38, v193, v38
	ds_bpermute_b32 v39, v193, v39
	s_waitcnt lgkmcnt(4)
	global_store_dwordx4 v[46:47], v[28:31], off
	s_waitcnt lgkmcnt(0)
	global_store_dwordx4 v[46:47], v[36:39], off offset:256
	v_lshl_add_u64 v[30:31], v[128:129], 0, v[160:161]
	s_nop 1
	v_mov_b32_e32 v28, v242
	v_fmamk_f32 v28, v28, 0x3a800000, v175
	v_rsq_f32_e32 v28, v28
	s_nop 0
	v_pk_mul_f32 v[34:35], v[34:35], v[28:29] op_sel_hi:[1,0]
	v_pk_mul_f32 v[32:33], v[32:33], v[28:29] op_sel_hi:[1,0]
	v_pk_mul_f32 v[26:27], v[26:27], v[28:29] op_sel_hi:[1,0]
	v_pk_mul_f32 v[24:25], v[24:25], v[28:29] op_sel_hi:[1,0]
	v_pk_mul_f32 v[22:23], v[22:23], v[28:29] op_sel_hi:[1,0]
	v_pk_mul_f32 v[20:21], v[20:21], v[28:29] op_sel_hi:[1,0]
	v_pk_mul_f32 v[36:37], v[14:15], v[28:29] op_sel_hi:[1,0]
	v_pk_mul_f32 v[28:29], v[12:13], v[28:29] op_sel_hi:[1,0]
	v_cvt_pk_bf16_f32 v12, v32, v33
	v_cvt_pk_bf16_f32 v13, v34, v35
	v_cvt_pk_bf16_f32 v14, v24, v25
	v_cvt_pk_bf16_f32 v15, v26, v27
	ds_bpermute_b32 v12, v193, v12
	ds_bpermute_b32 v13, v193, v13
	ds_bpermute_b32 v14, v193, v14
	ds_bpermute_b32 v15, v193, v15
	v_cvt_pk_bf16_f32 v20, v20, v21
	v_cvt_pk_bf16_f32 v21, v22, v23
	v_cvt_pk_bf16_f32 v22, v28, v29
	v_cvt_pk_bf16_f32 v23, v36, v37
	ds_bpermute_b32 v20, v193, v20
	ds_bpermute_b32 v21, v193, v21
	ds_bpermute_b32 v22, v193, v22
	ds_bpermute_b32 v23, v193, v23
	s_waitcnt lgkmcnt(4)
	global_store_dwordx4 v[30:31], v[12:15], off
	s_waitcnt lgkmcnt(0)
	global_store_dwordx4 v[30:31], v[20:23], off offset:256
	v_lshl_add_u64 v[14:15], v[128:129], 0, v[162:163]
	s_nop 1
	v_mov_b32_e32 v12, v243
	v_fmamk_f32 v12, v12, 0x3a800000, v175
	v_rsq_f32_e32 v12, v12
	s_nop 0
	v_pk_mul_f32 v[18:19], v[18:19], v[12:13] op_sel_hi:[1,0]
	v_pk_mul_f32 v[16:17], v[16:17], v[12:13] op_sel_hi:[1,0]
	v_pk_mul_f32 v[10:11], v[10:11], v[12:13] op_sel_hi:[1,0]
	v_pk_mul_f32 v[8:9], v[8:9], v[12:13] op_sel_hi:[1,0]
	v_pk_mul_f32 v[6:7], v[6:7], v[12:13] op_sel_hi:[1,0]
	v_pk_mul_f32 v[4:5], v[4:5], v[12:13] op_sel_hi:[1,0]
	v_pk_mul_f32 v[170:171], v[2:3], v[12:13] op_sel_hi:[1,0]
	v_pk_mul_f32 v[12:13], v[0:1], v[12:13] op_sel_hi:[1,0]
	v_cvt_pk_bf16_f32 v0, v16, v17
	v_cvt_pk_bf16_f32 v1, v18, v19
	v_cvt_pk_bf16_f32 v2, v8, v9
	v_cvt_pk_bf16_f32 v3, v10, v11
	ds_bpermute_b32 v0, v193, v0
	ds_bpermute_b32 v1, v193, v1
	ds_bpermute_b32 v2, v193, v2
	ds_bpermute_b32 v3, v193, v3
	v_cvt_pk_bf16_f32 v128, v4, v5
	v_cvt_pk_bf16_f32 v129, v6, v7
	v_cvt_pk_bf16_f32 v130, v12, v13
	s_waitcnt lgkmcnt(0)
	global_store_dwordx4 v[14:15], v[0:3], off
	s_branch .LBB0_748
